# P3 G23: stage sum-of-squares records in LDS via LDS-DMA at K-loop entry; epilogue rounds read them with ds_read (no vmcnt(0) per round)
# baseline (speedup 1.0000x reference)
.LBB0_1335:
	s_ashr_i32 s41, s40, 31
	s_lshl_b64 s[44:45], s[40:41], 17
	s_cmp_eq_u32 s75, 1
	s_cselect_b32 s2, s17, 0xc80000
	s_cselect_b32 s21, 0xc80000, s17
	s_cmp_eq_u32 s75, 0
	s_cselect_b32 s2, 0x3f00000, s2
	s_cselect_b32 s41, 0xc00000, s21
	s_add_u32 s2, s80, s2
	s_addc_u32 s21, s81, 0
	s_add_u32 s44, s2, s44
	s_addc_u32 s45, s21, s45
	s_ashr_i32 s21, s20, 31
	s_lshl_b64 s[46:47], s[20:21], 17
	s_add_u32 s2, s80, s41
	s_addc_u32 s21, s81, 0
	s_add_u32 s46, s2, s46
	v_mov_b32_e32 v125, 0
	s_addc_u32 s47, s21, s47
	s_andn2_b64 vcc, exec, s[24:25]
	v_mov_b32_e32 v124, v125
	v_mov_b32_e32 v123, v125
	v_mov_b32_e32 v122, v125
	v_mov_b32_e32 v129, v125
	v_mov_b32_e32 v128, v125
	v_mov_b32_e32 v127, v125
	v_mov_b32_e32 v126, v125
	v_mov_b32_e32 v121, v125
	v_mov_b32_e32 v120, v125
	v_mov_b32_e32 v119, v125
	v_mov_b32_e32 v118, v125
	v_mov_b32_e32 v117, v125
	v_mov_b32_e32 v116, v125
	v_mov_b32_e32 v115, v125
	v_mov_b32_e32 v114, v125
	v_mov_b32_e32 v113, v125
	v_mov_b32_e32 v112, v125
	v_mov_b32_e32 v111, v125
	v_mov_b32_e32 v110, v125
	v_mov_b32_e32 v109, v125
	v_mov_b32_e32 v108, v125
	v_mov_b32_e32 v107, v125
	v_mov_b32_e32 v106, v125
	v_mov_b32_e32 v105, v125
	v_mov_b32_e32 v104, v125
	v_mov_b32_e32 v103, v125
	v_mov_b32_e32 v102, v125
	v_mov_b32_e32 v101, v125
	v_mov_b32_e32 v100, v125
	v_mov_b32_e32 v99, v125
	v_mov_b32_e32 v98, v125
	v_mov_b32_e32 v65, v125
	v_mov_b32_e32 v64, v125
	v_mov_b32_e32 v63, v125
	v_mov_b32_e32 v62, v125
	v_mov_b32_e32 v61, v125
	v_mov_b32_e32 v60, v125
	v_mov_b32_e32 v59, v125
	v_mov_b32_e32 v58, v125
	v_mov_b32_e32 v57, v125
	v_mov_b32_e32 v56, v125
	v_mov_b32_e32 v55, v125
	v_mov_b32_e32 v54, v125
	v_mov_b32_e32 v53, v125
	v_mov_b32_e32 v52, v125
	v_mov_b32_e32 v51, v125
	v_mov_b32_e32 v50, v125
	v_mov_b32_e32 v49, v125
	v_mov_b32_e32 v48, v125
	v_mov_b32_e32 v47, v125
	v_mov_b32_e32 v46, v125
	v_mov_b32_e32 v45, v125
	v_mov_b32_e32 v44, v125
	v_mov_b32_e32 v43, v125
	v_mov_b32_e32 v42, v125
	v_mov_b32_e32 v41, v125
	v_mov_b32_e32 v40, v125
	v_mov_b32_e32 v39, v125
	v_mov_b32_e32 v38, v125
	v_mov_b32_e32 v37, v125
	v_mov_b32_e32 v36, v125
	v_mov_b32_e32 v35, v125
	v_mov_b32_e32 v34, v125
	v_mov_b32_e32 v97, v125
	v_mov_b32_e32 v96, v125
	v_mov_b32_e32 v95, v125
	v_mov_b32_e32 v94, v125
	v_mov_b32_e32 v93, v125
	v_mov_b32_e32 v92, v125
	v_mov_b32_e32 v91, v125
	v_mov_b32_e32 v90, v125
	v_mov_b32_e32 v89, v125
	v_mov_b32_e32 v88, v125
	v_mov_b32_e32 v87, v125
	v_mov_b32_e32 v86, v125
	v_mov_b32_e32 v85, v125
	v_mov_b32_e32 v84, v125
	v_mov_b32_e32 v83, v125
	v_mov_b32_e32 v82, v125
	v_mov_b32_e32 v81, v125
	v_mov_b32_e32 v80, v125
	v_mov_b32_e32 v79, v125
	v_mov_b32_e32 v78, v125
	v_mov_b32_e32 v77, v125
	v_mov_b32_e32 v76, v125
	v_mov_b32_e32 v75, v125
	v_mov_b32_e32 v74, v125
	v_mov_b32_e32 v73, v125
	v_mov_b32_e32 v72, v125
	v_mov_b32_e32 v71, v125
	v_mov_b32_e32 v70, v125
	v_mov_b32_e32 v69, v125
	v_mov_b32_e32 v68, v125
	v_mov_b32_e32 v67, v125
	v_mov_b32_e32 v66, v125
	v_mov_b32_e32 v33, v125
	v_mov_b32_e32 v32, v125
	v_mov_b32_e32 v31, v125
	v_mov_b32_e32 v30, v125
	v_mov_b32_e32 v29, v125
	v_mov_b32_e32 v28, v125
	v_mov_b32_e32 v27, v125
	v_mov_b32_e32 v26, v125
	v_mov_b32_e32 v25, v125
	v_mov_b32_e32 v24, v125
	v_mov_b32_e32 v23, v125
	v_mov_b32_e32 v22, v125
	v_mov_b32_e32 v21, v125
	v_mov_b32_e32 v20, v125
	v_mov_b32_e32 v19, v125
	v_mov_b32_e32 v18, v125
	v_mov_b32_e32 v17, v125
	v_mov_b32_e32 v16, v125
	v_mov_b32_e32 v15, v125
	v_mov_b32_e32 v14, v125
	v_mov_b32_e32 v13, v125
	v_mov_b32_e32 v12, v125
	v_mov_b32_e32 v11, v125
	v_mov_b32_e32 v10, v125
	v_mov_b32_e32 v9, v125
	v_mov_b32_e32 v8, v125
	v_mov_b32_e32 v7, v125
	v_mov_b32_e32 v6, v125
	v_mov_b32_e32 v5, v125
	v_mov_b32_e32 v4, v125
	v_mov_b32_e32 v3, v125
	v_mov_b32_e32 v2, v125
	s_cbranch_vccnz .LBB0_1338
	s_and_b64 s[50:51], s[42:43], exec
	s_cselect_b32 s2, s45, s9
	s_cselect_b32 s21, s44, s8
	s_cselect_b32 s41, s47, s11
	s_cselect_b32 s50, s46, s10
	s_add_u32 s8, s8, 0x80
	s_addc_u32 s9, s9, 0
	s_add_u32 s51, s10, 0x100
	v_mov_b32_e32 v2, 0
	s_addc_u32 s52, s11, 0
	s_mov_b32 s10, 0
	v_mov_b32_e32 v3, v2
	v_mov_b32_e32 v4, v2
	v_mov_b32_e32 v5, v2
	v_mov_b32_e32 v6, v2
	v_mov_b32_e32 v7, v2
	v_mov_b32_e32 v8, v2
	v_mov_b32_e32 v9, v2
	v_mov_b32_e32 v10, v2
	v_mov_b32_e32 v11, v2
	v_mov_b32_e32 v12, v2
	v_mov_b32_e32 v13, v2
	v_mov_b32_e32 v14, v2
	v_mov_b32_e32 v15, v2
	v_mov_b32_e32 v16, v2
	v_mov_b32_e32 v17, v2
	v_mov_b32_e32 v18, v2
	v_mov_b32_e32 v19, v2
	v_mov_b32_e32 v20, v2
	v_mov_b32_e32 v21, v2
	v_mov_b32_e32 v22, v2
	v_mov_b32_e32 v23, v2
	v_mov_b32_e32 v24, v2
	v_mov_b32_e32 v25, v2
	v_mov_b32_e32 v26, v2
	v_mov_b32_e32 v27, v2
	v_mov_b32_e32 v28, v2
	v_mov_b32_e32 v29, v2
	v_mov_b32_e32 v30, v2
	v_mov_b32_e32 v31, v2
	v_mov_b32_e32 v32, v2
	v_mov_b32_e32 v33, v2
	v_mov_b32_e32 v66, v2
	v_mov_b32_e32 v67, v2
	v_mov_b32_e32 v68, v2
	v_mov_b32_e32 v69, v2
	v_mov_b32_e32 v70, v2
	v_mov_b32_e32 v71, v2
	v_mov_b32_e32 v72, v2
	v_mov_b32_e32 v73, v2
	v_mov_b32_e32 v74, v2
	v_mov_b32_e32 v75, v2
	v_mov_b32_e32 v76, v2
	v_mov_b32_e32 v77, v2
	v_mov_b32_e32 v78, v2
	v_mov_b32_e32 v79, v2
	v_mov_b32_e32 v80, v2
	v_mov_b32_e32 v81, v2
	v_mov_b32_e32 v82, v2
	v_mov_b32_e32 v83, v2
	v_mov_b32_e32 v84, v2
	v_mov_b32_e32 v85, v2
	v_mov_b32_e32 v86, v2
	v_mov_b32_e32 v87, v2
	v_mov_b32_e32 v88, v2
	v_mov_b32_e32 v89, v2
	v_mov_b32_e32 v90, v2
	v_mov_b32_e32 v91, v2
	v_mov_b32_e32 v92, v2
	v_mov_b32_e32 v93, v2
	v_mov_b32_e32 v94, v2
	v_mov_b32_e32 v95, v2
	v_mov_b32_e32 v96, v2
	v_mov_b32_e32 v97, v2
	v_mov_b32_e32 v34, v2
	v_mov_b32_e32 v35, v2
	v_mov_b32_e32 v36, v2
	v_mov_b32_e32 v37, v2
	v_mov_b32_e32 v38, v2
	v_mov_b32_e32 v39, v2
	v_mov_b32_e32 v40, v2
	v_mov_b32_e32 v41, v2
	v_mov_b32_e32 v42, v2
	v_mov_b32_e32 v43, v2
	v_mov_b32_e32 v44, v2
	v_mov_b32_e32 v45, v2
	v_mov_b32_e32 v46, v2
	v_mov_b32_e32 v47, v2
	v_mov_b32_e32 v48, v2
	v_mov_b32_e32 v49, v2
	v_mov_b32_e32 v50, v2
	v_mov_b32_e32 v51, v2
	v_mov_b32_e32 v52, v2
	v_mov_b32_e32 v53, v2
	v_mov_b32_e32 v54, v2
	v_mov_b32_e32 v55, v2
	v_mov_b32_e32 v56, v2
	v_mov_b32_e32 v57, v2
	v_mov_b32_e32 v58, v2
	v_mov_b32_e32 v59, v2
	v_mov_b32_e32 v60, v2
	v_mov_b32_e32 v61, v2
	v_mov_b32_e32 v62, v2
	v_mov_b32_e32 v63, v2
	v_mov_b32_e32 v64, v2
	v_mov_b32_e32 v65, v2
	v_mov_b32_e32 v98, v2
	v_mov_b32_e32 v99, v2
	v_mov_b32_e32 v100, v2
	v_mov_b32_e32 v101, v2
	v_mov_b32_e32 v102, v2
	v_mov_b32_e32 v103, v2
	v_mov_b32_e32 v104, v2
	v_mov_b32_e32 v105, v2
	v_mov_b32_e32 v106, v2
	v_mov_b32_e32 v107, v2
	v_mov_b32_e32 v108, v2
	v_mov_b32_e32 v109, v2
	v_mov_b32_e32 v110, v2
	v_mov_b32_e32 v111, v2
	v_mov_b32_e32 v112, v2
	v_mov_b32_e32 v113, v2
	v_mov_b32_e32 v114, v2
	v_mov_b32_e32 v115, v2
	v_mov_b32_e32 v116, v2
	v_mov_b32_e32 v117, v2
	v_mov_b32_e32 v118, v2
	v_mov_b32_e32 v119, v2
	v_mov_b32_e32 v120, v2
	v_mov_b32_e32 v121, v2
	v_mov_b32_e32 v126, v2
	v_mov_b32_e32 v127, v2
	v_mov_b32_e32 v128, v2
	v_mov_b32_e32 v129, v2
	v_mov_b32_e32 v122, v2
	v_mov_b32_e32 v123, v2
	v_mov_b32_e32 v124, v2
	v_mov_b32_e32 v125, v2
	s_cmp_eq_u32 s3, 2
	s_cbranch_scc1 .Lsst3_k2
	s_cmp_eq_u32 s3, 0
	s_cselect_b32 s98, s34, s28
	s_cselect_b32 s99, s35, s29
	v_mbcnt_lo_u32_b32 v244, -1, 0
	v_mbcnt_hi_u32_b32 v244, -1, v244
	v_lshlrev_b32_e32 v244, 4, v244
	v_lshl_add_u32 v244, s62, 4, v244
	v_lshl_add_u32 v244, s48, 12, v244
	v_mov_b32_e32 v245, 0
	v_lshl_add_u64 v[244:245], v[244:245], 0, s[98:99]
	s_bitcmp1_b32 s56, 0
	s_cselect_b32 s98, 0x1000, 0
	s_add_i32 s99, s98, 0x20400
	v_mov_b32_e32 v247, s99
	s_lshl_b32 s98, s62, 4
	s_add_i32 m0, s98, s99
	s_nop 0
	global_load_lds_dwordx4 v[244:245], off
	global_load_lds_dwordx4 v[244:245], off offset:2048
	s_branch .Lsst3_done
.Lsst3_k2:
	s_mov_b32 s98, s28
	s_mov_b32 s99, s29
	v_mbcnt_lo_u32_b32 v244, -1, 0
	v_mbcnt_hi_u32_b32 v244, -1, v244
	v_and_b32_e32 v245, 4, v244
	v_and_b32_e32 v244, 3, v244
	v_lshlrev_b32_e32 v245, 9, v245
	v_lshl_or_b32 v244, v244, 7, v245
	v_lshl_add_u32 v244, s63, 4, v244
	v_lshl_add_u32 v244, s38, 12, v244
	v_mov_b32_e32 v245, 0
	s_mov_b32 m0, 0x22800
	v_lshl_add_u64 v[244:245], v[244:245], 0, s[98:99]
	global_load_lds_dword v[244:245], off
.Lsst3_done:
.LBB0_1337:
	ds_read_b128 v[150:153], v172
	ds_read_b128 v[154:157], v172 offset:1024
	ds_read_b128 v[158:161], v172 offset:2048
	ds_read_b128 v[162:165], v172 offset:3072
	ds_read_b128 v[180:183], v173
	ds_read_b128 v[184:187], v173 offset:1024
	ds_read_b128 v[188:191], v173 offset:2048
	ds_read_b128 v[192:195], v173 offset:3072
	s_add_i32 s53, s10, 2
	s_add_u32 s54, s8, 0x80
	s_addc_u32 s11, s9, 0
	s_cmp_eq_u32 s64, s10
	s_cselect_b32 s10, s21, s54
	s_cselect_b32 s11, s2, s11
	s_cselect_b32 s55, s41, s52
	s_cselect_b32 s54, s50, s51
	s_cbranch_scc0 .Lpf_skip_2
	s_getpc_b64 s[98:99]
	s_mov_b32 m0, 0x22800
	v_lshlrev_b32_e32 v196, 7, v0
	global_load_lds_dword v196, s[98:99]

.LBB0_1347:
	s_lshl_b32 s2, s48, 8
	s_add_i32 s2, s2, s62
	v_or_b32_e32 v150, s2, v1
	v_cmp_lt_i32_e32 vcc, s70, v150
	s_and_saveexec_b64 s[8:9], vcc
	s_xor_b64 s[8:9], exec, s[8:9]
	s_add_i32 s10, s2, 0xffffc000
	s_lshr_b32 s10, s10, 8
	v_and_b32_e32 v138, 0xcf, v150
	v_or_b32_e32 v138, 0x1000, v138
	v_mov_b32_e32 v154, s10
	s_andn2_saveexec_b64 s[8:9], s[8:9]
	s_ashr_i32 s10, s2, 12
	v_and_b32_e32 v138, 0xfcf, v150
	v_mov_b32_e32 v154, s10
	s_or_b64 exec, exec, s[8:9]
	s_cmp_lg_u32 s3, 0
	s_cselect_b64 s[50:51], -1, 0
	v_ashrrev_i32_e32 v151, 31, v150
	v_lshlrev_b64 v[152:153], 4, v[150:151]
	s_and_b64 vcc, exec, s[50:51]
	s_cbranch_vccz .LBB0_1353
	v_and_b32_e32 v246, 0xff0, v152
	v_lshl_add_u64 v[156:157], s[28:29], 0, v[152:153]
	v_add_u32_e32 v246, v247, v246
	ds_read_b128 v[156:159], v246
	s_lshl_b32 s3, s38, 8
	s_or_b32 s3, s3, s63
	s_ashr_i32 s3, s3, 6
	v_lshl_add_u32 v151, v154, 3, s3
	v_mad_i64_i32 v[160:161], s[8:9], v151, s72, v[138:139]
	v_or_b32_e32 v151, 2, v151
	v_mad_i64_i32 v[162:163], s[8:9], v151, s72, v[138:139]
	v_mad_u64_u32 v[164:165], s[8:9], v160, s49, v[140:141]
	v_mad_i32_i24 v165, v161, s49, v165
	s_waitcnt lgkmcnt(0)
	v_mov_b32_e32 v180, v157
	v_mov_b32_e32 v181, v158
	v_mov_b32_e32 v157, v159
	v_pk_add_f32 v[156:157], v[180:181], v[156:157]
	v_mad_u64_u32 v[180:181], s[8:9], v162, s49, v[140:141]
	v_add_f32_e32 v151, v156, v157
	v_fmamk_f32 v151, v151, 0x3c000000, v175
	v_mul_f32_e32 v155, 0x4f800000, v151
	v_cmp_gt_f32_e32 vcc, s71, v151
	v_mad_i32_i24 v181, v163, s49, v181
	s_nop 0
	v_cndmask_b32_e32 v151, v151, v155, vcc
	v_sqrt_f32_e32 v155, v151
	s_nop 0
	v_add_u32_e32 v156, -1, v155
	v_add_u32_e32 v157, 1, v155
	v_fma_f32 v158, -v156, v155, v151
	v_fma_f32 v159, -v157, v155, v151
	v_cmp_ge_f32_e64 s[8:9], 0, v158
	s_nop 1
	v_cndmask_b32_e64 v155, v155, v156, s[8:9]
	v_cmp_lt_f32_e64 s[8:9], 0, v159
	s_nop 1
	v_cndmask_b32_e64 v155, v155, v157, s[8:9]
	v_mul_f32_e32 v156, 0x37800000, v155
	v_cndmask_b32_e32 v155, v155, v156, vcc
	v_cmp_class_f32_e32 vcc, v151, v176
	s_nop 1
	v_cndmask_b32_e32 v151, v155, v151, vcc
	v_div_scale_f32 v155, s[8:9], v151, v151, 1.0
	v_rcp_f32_e32 v156, v155
	v_div_scale_f32 v157, vcc, 1.0, v151, 1.0
	v_fma_f32 v158, -v155, v156, 1.0
	v_fmac_f32_e32 v156, v158, v156
	v_mul_f32_e32 v158, v157, v156
	v_fma_f32 v159, -v155, v158, v157
	v_fmac_f32_e32 v158, v159, v156
	v_fma_f32 v155, -v155, v158, v157
	v_div_fmas_f32 v155, v155, v156, v158
	v_div_fixup_f32 v156, v155, v151, 1.0
	v_pk_mul_f32 v[158:159], v[124:125], v[156:157] op_sel_hi:[1,0]
	v_pk_mul_f32 v[160:161], v[122:123], v[156:157] op_sel_hi:[1,0]
	v_pk_mul_f32 v[162:163], v[128:129], v[156:157] op_sel_hi:[1,0]
	v_pk_mul_f32 v[182:183], v[126:127], v[156:157] op_sel_hi:[1,0]
	v_pk_mul_f32 v[184:185], v[64:65], v[156:157] op_sel_hi:[1,0]
	v_pk_mul_f32 v[186:187], v[62:63], v[156:157] op_sel_hi:[1,0]
	v_pk_mul_f32 v[188:189], v[60:61], v[156:157] op_sel_hi:[1,0]
	v_pk_mul_f32 v[190:191], v[58:59], v[156:157] op_sel_hi:[1,0]
	v_cvt_pk_bf16_f32 v156, v160, v161
	v_cvt_pk_bf16_f32 v157, v158, v159
	v_cvt_pk_bf16_f32 v158, v182, v183
	v_cvt_pk_bf16_f32 v159, v162, v163
	v_cvt_pk_bf16_f32 v160, v186, v187
	v_cvt_pk_bf16_f32 v161, v184, v185
	v_cvt_pk_bf16_f32 v162, v190, v191
	v_cvt_pk_bf16_f32 v163, v188, v189
	global_store_dwordx4 v[164:165], v[156:159], off
	global_store_dwordx4 v[180:181], v[160:163], off
	s_cbranch_execz .LBB0_1354
	s_branch .LBB0_1362
.LBB0_1353:
.LBB0_1354:
	v_and_b32_e32 v246, 0xff0, v152
	v_lshl_add_u64 v[152:153], s[34:35], 0, v[152:153]
	v_add_u32_e32 v246, v247, v246
	ds_read_b128 v[156:159], v246
	v_lshlrev_b32_e32 v151, 3, v154
	v_lshrrev_b32_e32 v152, 6, v138
	v_and_b32_e32 v153, 63, v138
	v_cndmask_b32_e64 v153, v153, v152, s[0:1]
	s_cmp_gt_i32 s38, 1
	s_cselect_b64 s[52:53], -1, 0
	v_mov_b32_e32 v155, v139
	s_and_b64 s[8:9], exec, s[52:53]
	s_mov_b64 s[54:55], -1
	v_or_b32_e32 v152, s60, v151
	s_waitcnt lgkmcnt(0)
	v_mov_b32_e32 v160, v157
	v_mov_b32_e32 v161, v158
	v_mov_b32_e32 v157, v159
	v_pk_add_f32 v[156:157], v[160:161], v[156:157]
	s_nop 0
	v_add_f32_e32 v154, v156, v157
	v_fmamk_f32 v154, v154, 0x3b800000, v175
	v_mul_f32_e32 v156, 0x4f800000, v154
	v_cmp_gt_f32_e32 vcc, s71, v154
	s_nop 1
	v_cndmask_b32_e32 v156, v154, v156, vcc
	v_sqrt_f32_e32 v157, v156
	v_lshlrev_b32_e32 v154, 6, v153
	v_lshl_add_u64 v[154:155], s[30:31], 0, v[154:155]
	v_add_u32_e32 v153, -1, v157
	v_add_u32_e32 v158, 1, v157
	v_fma_f32 v159, -v153, v157, v156
	v_fma_f32 v160, -v158, v157, v156
	v_cmp_ge_f32_e64 s[10:11], 0, v159
	s_nop 1
	v_cndmask_b32_e64 v153, v157, v153, s[10:11]
	v_cmp_lt_f32_e64 s[10:11], 0, v160
	s_nop 1
	v_cndmask_b32_e64 v153, v153, v158, s[10:11]
	v_mul_f32_e32 v157, 0x37800000, v153
	v_cndmask_b32_e32 v153, v153, v157, vcc
	v_cmp_class_f32_e32 vcc, v156, v176
	s_nop 1
	v_cndmask_b32_e32 v153, v153, v156, vcc
	v_div_scale_f32 v156, s[10:11], v153, v153, s73
	v_rcp_f32_e32 v157, v156
	v_div_scale_f32 v158, vcc, s73, v153, s73
	v_fma_f32 v159, -v156, v157, 1.0
	v_fmac_f32_e32 v157, v159, v157
	v_mul_f32_e32 v159, v158, v157
	v_fma_f32 v160, -v156, v159, v158
	v_fmac_f32_e32 v159, v160, v157
	v_fma_f32 v156, -v156, v159, v158
	v_div_fmas_f32 v156, v156, v157, v159
	v_div_fixup_f32 v156, v156, v153, s73
	v_pk_mul_f32 v[160:161], v[124:125], v[156:157] op_sel_hi:[1,0]
	v_pk_mul_f32 v[164:165], v[122:123], v[156:157] op_sel_hi:[1,0]
	v_pk_mul_f32 v[158:159], v[128:129], v[156:157] op_sel_hi:[1,0]
	v_pk_mul_f32 v[162:163], v[126:127], v[156:157] op_sel_hi:[1,0]
	s_mov_b64 vcc, s[8:9]
	s_cbranch_vccz .LBB0_1356
	global_load_dwordx4 v[180:183], v[154:155], off
	global_load_dwordx4 v[184:187], v[154:155], off offset:16
	global_load_dwordx4 v[188:191], v[154:155], off offset:32
	global_load_dwordx4 v[192:195], v[154:155], off offset:48
	v_and_b32_e32 v179, 64, v177
	v_xor_b32_e32 v157, 16, v177
	v_add_u32_e32 v179, 64, v179
	v_ashrrev_i32_e32 v153, 31, v152
	v_cmp_lt_i32_e32 vcc, v157, v179
	v_lshlrev_b64 v[196:197], 12, v[152:153]
	v_lshl_add_u64 v[196:197], v[196:197], 0, v[138:139]
	v_cndmask_b32_e32 v153, v177, v157, vcc
	v_lshlrev_b32_e32 v153, 2, v153
	ds_bpermute_b32 v157, v153, v164
	ds_bpermute_b32 v179, v153, v165
	ds_bpermute_b32 v199, v153, v160
	ds_bpermute_b32 v202, v153, v161
	ds_bpermute_b32 v204, v153, v162
	ds_bpermute_b32 v205, v153, v163
	ds_bpermute_b32 v206, v153, v158
	ds_bpermute_b32 v153, v153, v159
	v_mad_u64_u32 v[200:201], s[8:9], v196, s49, v[144:145]
	v_mad_i32_i24 v201, v197, s49, v201
	s_waitcnt lgkmcnt(0)
	v_cndmask_b32_e64 v197, v179, -v179, s[4:5]
	v_cndmask_b32_e64 v196, v157, -v157, s[4:5]
	v_cndmask_b32_e64 v203, v202, -v202, s[4:5]
	v_cndmask_b32_e64 v202, v199, -v199, s[4:5]
	v_cndmask_b32_e64 v205, v205, -v205, s[4:5]
	v_cndmask_b32_e64 v204, v204, -v204, s[4:5]
	v_cndmask_b32_e64 v207, v153, -v153, s[4:5]
	v_cndmask_b32_e64 v206, v206, -v206, s[4:5]
	s_mov_b64 s[54:55], 0
	s_waitcnt vmcnt(3)
	v_mov_b32_e32 v209, v182
	v_mov_b32_e32 v182, v181
	s_waitcnt vmcnt(2)
	v_mov_b32_e32 v181, v186
	v_mov_b32_e32 v186, v185
	s_waitcnt vmcnt(1)
	v_mov_b32_e32 v185, v190
	v_mov_b32_e32 v190, v189
	s_waitcnt vmcnt(0)
	v_mov_b32_e32 v189, v194
	v_mov_b32_e32 v194, v193
	v_mov_b32_e32 v208, v180
	v_mov_b32_e32 v180, v184
	v_mov_b32_e32 v184, v188
	v_mov_b32_e32 v188, v192
	v_pk_mul_f32 v[182:183], v[196:197], v[182:183]
	v_pk_mul_f32 v[186:187], v[202:203], v[186:187]
	v_pk_mul_f32 v[190:191], v[204:205], v[190:191]
	v_pk_mul_f32 v[192:193], v[206:207], v[194:195]
	v_pk_fma_f32 v[182:183], v[164:165], v[208:209], v[182:183]
	v_pk_fma_f32 v[186:187], v[160:161], v[180:181], v[186:187]
	v_pk_fma_f32 v[184:185], v[162:163], v[184:185], v[190:191]
	v_pk_fma_f32 v[188:189], v[158:159], v[188:189], v[192:193]
	v_cvt_pk_bf16_f32 v180, v182, v183
	v_cvt_pk_bf16_f32 v181, v186, v187
	v_cvt_pk_bf16_f32 v182, v184, v185
	v_cvt_pk_bf16_f32 v183, v188, v189
	global_store_dwordx4 v[200:201], v[180:183], off offset:128

.LBB0_1362:
	s_nop 1
	v_or_b32_e32 v152, 16, v150
	v_cmp_lt_i32_e32 vcc, s70, v152
	s_and_saveexec_b64 s[8:9], vcc
	s_xor_b64 s[8:9], exec, s[8:9]
	s_add_i32 s3, s2, 0xffffc000
	s_lshr_b32 s3, s3, 8
	v_and_b32_e32 v138, 0xdf, v152
	v_or_b32_e32 v138, 0x1000, v138
	v_mov_b32_e32 v151, s3
	s_andn2_saveexec_b64 s[8:9], s[8:9]
	s_ashr_i32 s3, s2, 12
	v_and_b32_e32 v138, 0xfdf, v152
	v_mov_b32_e32 v151, s3
	s_or_b64 exec, exec, s[8:9]
	v_ashrrev_i32_e32 v153, 31, v152
	v_cndmask_b32_e64 v154, 0, 1, s[50:51]
	v_cmp_ne_u32_e64 s[8:9], 1, v154
	s_andn2_b64 vcc, exec, s[50:51]
	v_lshlrev_b64 v[152:153], 4, v[152:153]
	s_cbranch_vccnz .LBB0_1368
	v_and_b32_e32 v246, 0xff0, v152
	v_lshl_add_u64 v[154:155], s[28:29], 0, v[152:153]
	v_add_u32_e32 v246, v247, v246
	ds_read_b128 v[154:157], v246
	s_lshl_b32 s3, s38, 8
	s_or_b32 s3, s3, s63
	s_ashr_i32 s3, s3, 6
	v_lshl_add_u32 v160, v151, 3, s3
	v_mad_i64_i32 v[158:159], s[10:11], v160, s72, v[138:139]
	v_or_b32_e32 v160, 2, v160
	v_mad_i64_i32 v[160:161], s[10:11], v160, s72, v[138:139]
	v_mad_u64_u32 v[162:163], s[10:11], v158, s49, v[140:141]
	v_mad_i32_i24 v163, v159, s49, v163
	s_waitcnt lgkmcnt(0)
	v_mov_b32_e32 v164, v155
	v_mov_b32_e32 v165, v156
	v_mov_b32_e32 v155, v157
	v_pk_add_f32 v[154:155], v[164:165], v[154:155]
	v_mad_u64_u32 v[164:165], s[10:11], v160, s49, v[140:141]
	v_add_f32_e32 v154, v154, v155
	v_fmamk_f32 v154, v154, 0x3c000000, v175
	v_mul_f32_e32 v155, 0x4f800000, v154
	v_cmp_gt_f32_e32 vcc, s71, v154
	v_mad_i32_i24 v165, v161, s49, v165
	s_nop 0
	v_cndmask_b32_e32 v154, v154, v155, vcc
	v_sqrt_f32_e32 v155, v154
	s_nop 0
	v_add_u32_e32 v156, -1, v155
	v_add_u32_e32 v157, 1, v155
	v_fma_f32 v158, -v156, v155, v154
	v_fma_f32 v159, -v157, v155, v154
	v_cmp_ge_f32_e64 s[10:11], 0, v158
	s_nop 1
	v_cndmask_b32_e64 v155, v155, v156, s[10:11]
	v_cmp_lt_f32_e64 s[10:11], 0, v159
	s_nop 1
	v_cndmask_b32_e64 v155, v155, v157, s[10:11]
	v_mul_f32_e32 v156, 0x37800000, v155
	v_cndmask_b32_e32 v155, v155, v156, vcc
	v_cmp_class_f32_e32 vcc, v154, v176
	s_nop 1
	v_cndmask_b32_e32 v154, v155, v154, vcc
	v_div_scale_f32 v155, s[10:11], v154, v154, 1.0
	v_rcp_f32_e32 v156, v155
	v_div_scale_f32 v157, vcc, 1.0, v154, 1.0
	v_fma_f32 v158, -v155, v156, 1.0
	v_fmac_f32_e32 v156, v158, v156
	v_mul_f32_e32 v158, v157, v156
	v_fma_f32 v159, -v155, v158, v157
	v_fmac_f32_e32 v158, v159, v156
	v_fma_f32 v155, -v155, v158, v157
	v_div_fmas_f32 v155, v155, v156, v158
	v_div_fixup_f32 v154, v155, v154, 1.0
	v_pk_mul_f32 v[156:157], v[120:121], v[154:155] op_sel_hi:[1,0]
	v_pk_mul_f32 v[158:159], v[118:119], v[154:155] op_sel_hi:[1,0]
	v_pk_mul_f32 v[160:161], v[116:117], v[154:155] op_sel_hi:[1,0]
	v_pk_mul_f32 v[180:181], v[114:115], v[154:155] op_sel_hi:[1,0]
	v_pk_mul_f32 v[182:183], v[56:57], v[154:155] op_sel_hi:[1,0]
	v_pk_mul_f32 v[184:185], v[54:55], v[154:155] op_sel_hi:[1,0]
	v_pk_mul_f32 v[186:187], v[52:53], v[154:155] op_sel_hi:[1,0]
	v_pk_mul_f32 v[188:189], v[50:51], v[154:155] op_sel_hi:[1,0]
	v_cvt_pk_bf16_f32 v154, v158, v159
	v_cvt_pk_bf16_f32 v155, v156, v157
	v_cvt_pk_bf16_f32 v156, v180, v181
	v_cvt_pk_bf16_f32 v157, v160, v161
	v_cvt_pk_bf16_f32 v158, v184, v185
	v_cvt_pk_bf16_f32 v159, v182, v183
	v_cvt_pk_bf16_f32 v160, v188, v189
	v_cvt_pk_bf16_f32 v161, v186, v187
	global_store_dwordx4 v[162:163], v[154:157], off
	global_store_dwordx4 v[164:165], v[158:161], off
	s_cbranch_execz .LBB0_1369
	s_branch .LBB0_1377
.LBB0_1368:
.LBB0_1369:
	v_and_b32_e32 v246, 0xff0, v152
	v_lshl_add_u64 v[152:153], s[34:35], 0, v[152:153]
	v_add_u32_e32 v246, v247, v246
	ds_read_b128 v[154:157], v246
	v_lshrrev_b32_e32 v152, 6, v138
	v_and_b32_e32 v153, 63, v138
	v_cndmask_b32_e64 v153, v153, v152, s[0:1]
	v_lshlrev_b32_e32 v158, 6, v153
	v_mov_b32_e32 v159, v139
	v_lshlrev_b32_e32 v151, 3, v151
	s_cmp_gt_i32 s38, 1
	v_or_b32_e32 v152, s60, v151
	s_cselect_b64 s[50:51], -1, 0
	s_cmp_lt_i32 s38, 2
	s_waitcnt lgkmcnt(0)
	v_mov_b32_e32 v160, v155
	v_mov_b32_e32 v161, v156
	v_mov_b32_e32 v155, v157
	v_pk_add_f32 v[154:155], v[160:161], v[154:155]
	s_nop 0
	v_add_f32_e32 v154, v154, v155
	v_fmamk_f32 v154, v154, 0x3b800000, v175
	v_mul_f32_e32 v155, 0x4f800000, v154
	v_cmp_gt_f32_e32 vcc, s71, v154
	s_nop 1
	v_cndmask_b32_e32 v154, v154, v155, vcc
	v_sqrt_f32_e32 v155, v154
	s_nop 0
	v_add_u32_e32 v153, -1, v155
	v_add_u32_e32 v156, 1, v155
	v_fma_f32 v157, -v153, v155, v154
	v_fma_f32 v160, -v156, v155, v154
	v_cmp_ge_f32_e64 s[10:11], 0, v157
	s_nop 1
	v_cndmask_b32_e64 v153, v155, v153, s[10:11]
	v_cmp_lt_f32_e64 s[10:11], 0, v160
	s_nop 1
	v_cndmask_b32_e64 v153, v153, v156, s[10:11]
	v_mul_f32_e32 v155, 0x37800000, v153
	v_cndmask_b32_e32 v153, v153, v155, vcc
	v_cmp_class_f32_e32 vcc, v154, v176
	s_nop 1
	v_cndmask_b32_e32 v153, v153, v154, vcc
	v_div_scale_f32 v156, s[10:11], v153, v153, s73
	v_rcp_f32_e32 v157, v156
	v_lshl_add_u64 v[154:155], s[30:31], 0, v[158:159]
	v_div_scale_f32 v158, vcc, s73, v153, s73
	v_fma_f32 v159, -v156, v157, 1.0
	v_fmac_f32_e32 v157, v159, v157
	v_mul_f32_e32 v159, v158, v157
	v_fma_f32 v160, -v156, v159, v158
	v_fmac_f32_e32 v159, v160, v157
	v_fma_f32 v156, -v156, v159, v158
	v_div_fmas_f32 v156, v156, v157, v159
	v_div_fixup_f32 v156, v156, v153, s73
	v_pk_mul_f32 v[160:161], v[120:121], v[156:157] op_sel_hi:[1,0]
	v_pk_mul_f32 v[164:165], v[118:119], v[156:157] op_sel_hi:[1,0]
	v_pk_mul_f32 v[158:159], v[116:117], v[156:157] op_sel_hi:[1,0]
	v_pk_mul_f32 v[162:163], v[114:115], v[156:157] op_sel_hi:[1,0]
	s_mov_b64 s[10:11], -1
	s_cbranch_scc1 .LBB0_1371
	global_load_dwordx4 v[180:183], v[154:155], off
	global_load_dwordx4 v[184:187], v[154:155], off offset:16
	global_load_dwordx4 v[188:191], v[154:155], off offset:32
	global_load_dwordx4 v[192:195], v[154:155], off offset:48
	v_and_b32_e32 v179, 64, v177
	v_xor_b32_e32 v157, 16, v177
	v_add_u32_e32 v179, 64, v179
	v_ashrrev_i32_e32 v153, 31, v152
	v_cmp_lt_i32_e32 vcc, v157, v179
	v_lshlrev_b64 v[196:197], 12, v[152:153]
	v_lshl_add_u64 v[196:197], v[196:197], 0, v[138:139]
	v_cndmask_b32_e32 v153, v177, v157, vcc
	v_lshlrev_b32_e32 v153, 2, v153
	ds_bpermute_b32 v157, v153, v164
	ds_bpermute_b32 v179, v153, v165
	ds_bpermute_b32 v199, v153, v160
	ds_bpermute_b32 v202, v153, v161
	ds_bpermute_b32 v204, v153, v162
	ds_bpermute_b32 v205, v153, v163
	ds_bpermute_b32 v206, v153, v158
	ds_bpermute_b32 v153, v153, v159
	v_mad_u64_u32 v[200:201], s[10:11], v196, s49, v[144:145]
	v_mad_i32_i24 v201, v197, s49, v201
	s_waitcnt lgkmcnt(0)
	v_cndmask_b32_e64 v197, v179, -v179, s[4:5]
	v_cndmask_b32_e64 v196, v157, -v157, s[4:5]
	v_cndmask_b32_e64 v203, v202, -v202, s[4:5]
	v_cndmask_b32_e64 v202, v199, -v199, s[4:5]
	v_cndmask_b32_e64 v205, v205, -v205, s[4:5]
	v_cndmask_b32_e64 v204, v204, -v204, s[4:5]
	v_cndmask_b32_e64 v207, v153, -v153, s[4:5]
	v_cndmask_b32_e64 v206, v206, -v206, s[4:5]
	s_mov_b64 s[10:11], 0
	s_waitcnt vmcnt(3)
	v_mov_b32_e32 v209, v182
	v_mov_b32_e32 v182, v181
	s_waitcnt vmcnt(2)
	v_mov_b32_e32 v181, v186
	v_mov_b32_e32 v186, v185
	s_waitcnt vmcnt(1)
	v_mov_b32_e32 v185, v190
	v_mov_b32_e32 v190, v189
	s_waitcnt vmcnt(0)
	v_mov_b32_e32 v189, v194
	v_mov_b32_e32 v194, v193
	v_mov_b32_e32 v208, v180
	v_mov_b32_e32 v180, v184
	v_mov_b32_e32 v184, v188
	v_mov_b32_e32 v188, v192
	v_pk_mul_f32 v[182:183], v[196:197], v[182:183]
	v_pk_mul_f32 v[186:187], v[202:203], v[186:187]
	v_pk_mul_f32 v[190:191], v[204:205], v[190:191]
	v_pk_mul_f32 v[192:193], v[206:207], v[194:195]
	v_pk_fma_f32 v[182:183], v[164:165], v[208:209], v[182:183]
	v_pk_fma_f32 v[186:187], v[160:161], v[180:181], v[186:187]
	v_pk_fma_f32 v[184:185], v[162:163], v[184:185], v[190:191]
	v_pk_fma_f32 v[188:189], v[158:159], v[188:189], v[192:193]
	v_cvt_pk_bf16_f32 v180, v182, v183
	v_cvt_pk_bf16_f32 v181, v186, v187
	v_cvt_pk_bf16_f32 v182, v184, v185
	v_cvt_pk_bf16_f32 v183, v188, v189
	global_store_dwordx4 v[200:201], v[180:183], off offset:128

.LBB0_1377:
	s_nop 1
	v_or_b32_e32 v152, 32, v150
	v_cmp_lt_i32_e32 vcc, s70, v152
	s_and_saveexec_b64 s[10:11], vcc
	s_xor_b64 s[10:11], exec, s[10:11]
	s_add_i32 s3, s2, 0xffffc000
	s_lshr_b32 s3, s3, 8
	v_and_b32_e32 v138, 0xef, v152
	v_or_b32_e32 v138, 0x1000, v138
	v_mov_b32_e32 v151, s3
	s_andn2_saveexec_b64 s[10:11], s[10:11]
	s_ashr_i32 s3, s2, 12
	v_and_b32_e32 v138, 0xfef, v152
	v_mov_b32_e32 v151, s3
	s_or_b64 exec, exec, s[10:11]
	v_ashrrev_i32_e32 v153, 31, v152
	s_and_b64 vcc, exec, s[8:9]
	v_lshlrev_b64 v[152:153], 4, v[152:153]
	s_cbranch_vccnz .LBB0_1383
	v_and_b32_e32 v246, 0xff0, v152
	v_lshl_add_u64 v[154:155], s[28:29], 0, v[152:153]
	v_add_u32_e32 v246, v247, v246
	ds_read_b128 v[154:157], v246
	s_lshl_b32 s3, s38, 8
	s_or_b32 s3, s3, s63
	s_ashr_i32 s3, s3, 6
	v_lshl_add_u32 v160, v151, 3, s3
	v_mad_i64_i32 v[158:159], s[10:11], v160, s72, v[138:139]
	v_or_b32_e32 v160, 2, v160
	v_mad_i64_i32 v[160:161], s[10:11], v160, s72, v[138:139]
	v_mad_u64_u32 v[162:163], s[10:11], v158, s49, v[140:141]
	v_mad_i32_i24 v163, v159, s49, v163
	s_waitcnt lgkmcnt(0)
	v_mov_b32_e32 v164, v155
	v_mov_b32_e32 v165, v156
	v_mov_b32_e32 v155, v157
	v_pk_add_f32 v[154:155], v[164:165], v[154:155]
	v_mad_u64_u32 v[164:165], s[10:11], v160, s49, v[140:141]
	v_add_f32_e32 v154, v154, v155
	v_fmamk_f32 v154, v154, 0x3c000000, v175
	v_mul_f32_e32 v155, 0x4f800000, v154
	v_cmp_gt_f32_e32 vcc, s71, v154
	v_mad_i32_i24 v165, v161, s49, v165
	s_nop 0
	v_cndmask_b32_e32 v154, v154, v155, vcc
	v_sqrt_f32_e32 v155, v154
	s_nop 0
	v_add_u32_e32 v156, -1, v155
	v_add_u32_e32 v157, 1, v155
	v_fma_f32 v158, -v156, v155, v154
	v_fma_f32 v159, -v157, v155, v154
	v_cmp_ge_f32_e64 s[10:11], 0, v158
	s_nop 1
	v_cndmask_b32_e64 v155, v155, v156, s[10:11]
	v_cmp_lt_f32_e64 s[10:11], 0, v159
	s_nop 1
	v_cndmask_b32_e64 v155, v155, v157, s[10:11]
	v_mul_f32_e32 v156, 0x37800000, v155
	v_cndmask_b32_e32 v155, v155, v156, vcc
	v_cmp_class_f32_e32 vcc, v154, v176
	s_nop 1
	v_cndmask_b32_e32 v154, v155, v154, vcc
	v_div_scale_f32 v155, s[10:11], v154, v154, 1.0
	v_rcp_f32_e32 v156, v155
	v_div_scale_f32 v157, vcc, 1.0, v154, 1.0
	v_fma_f32 v158, -v155, v156, 1.0
	v_fmac_f32_e32 v156, v158, v156
	v_mul_f32_e32 v158, v157, v156
	v_fma_f32 v159, -v155, v158, v157
	v_fmac_f32_e32 v158, v159, v156
	v_fma_f32 v155, -v155, v158, v157
	v_div_fmas_f32 v155, v155, v156, v158
	v_div_fixup_f32 v154, v155, v154, 1.0
	v_pk_mul_f32 v[156:157], v[112:113], v[154:155] op_sel_hi:[1,0]
	v_pk_mul_f32 v[158:159], v[110:111], v[154:155] op_sel_hi:[1,0]
	v_pk_mul_f32 v[160:161], v[108:109], v[154:155] op_sel_hi:[1,0]
	v_pk_mul_f32 v[180:181], v[106:107], v[154:155] op_sel_hi:[1,0]
	v_pk_mul_f32 v[182:183], v[48:49], v[154:155] op_sel_hi:[1,0]
	v_pk_mul_f32 v[184:185], v[46:47], v[154:155] op_sel_hi:[1,0]
	v_pk_mul_f32 v[186:187], v[44:45], v[154:155] op_sel_hi:[1,0]
	v_pk_mul_f32 v[188:189], v[42:43], v[154:155] op_sel_hi:[1,0]
	v_cvt_pk_bf16_f32 v154, v158, v159
	v_cvt_pk_bf16_f32 v155, v156, v157
	v_cvt_pk_bf16_f32 v156, v180, v181
	v_cvt_pk_bf16_f32 v157, v160, v161
	v_cvt_pk_bf16_f32 v158, v184, v185
	v_cvt_pk_bf16_f32 v159, v182, v183
	v_cvt_pk_bf16_f32 v160, v188, v189
	v_cvt_pk_bf16_f32 v161, v186, v187
	global_store_dwordx4 v[162:163], v[154:157], off
	global_store_dwordx4 v[164:165], v[158:161], off
	s_cbranch_execz .LBB0_1384
	s_branch .LBB0_1392
.LBB0_1383:
.LBB0_1384:
	v_and_b32_e32 v246, 0xff0, v152
	v_lshl_add_u64 v[152:153], s[34:35], 0, v[152:153]
	v_add_u32_e32 v246, v247, v246
	ds_read_b128 v[154:157], v246
	v_lshrrev_b32_e32 v152, 6, v138
	v_and_b32_e32 v153, 63, v138
	v_cndmask_b32_e64 v153, v153, v152, s[0:1]
	v_lshlrev_b32_e32 v158, 6, v153
	v_mov_b32_e32 v159, v139
	v_lshlrev_b32_e32 v151, 3, v151
	s_cmp_gt_i32 s38, 1
	v_or_b32_e32 v152, s60, v151
	s_cselect_b64 s[50:51], -1, 0
	s_cmp_lt_i32 s38, 2
	s_waitcnt lgkmcnt(0)
	v_mov_b32_e32 v160, v155
	v_mov_b32_e32 v161, v156
	v_mov_b32_e32 v155, v157
	v_pk_add_f32 v[154:155], v[160:161], v[154:155]
	s_nop 0
	v_add_f32_e32 v154, v154, v155
	v_fmamk_f32 v154, v154, 0x3b800000, v175
	v_mul_f32_e32 v155, 0x4f800000, v154
	v_cmp_gt_f32_e32 vcc, s71, v154
	s_nop 1
	v_cndmask_b32_e32 v154, v154, v155, vcc
	v_sqrt_f32_e32 v155, v154
	s_nop 0
	v_add_u32_e32 v153, -1, v155
	v_add_u32_e32 v156, 1, v155
	v_fma_f32 v157, -v153, v155, v154
	v_fma_f32 v160, -v156, v155, v154
	v_cmp_ge_f32_e64 s[10:11], 0, v157
	s_nop 1
	v_cndmask_b32_e64 v153, v155, v153, s[10:11]
	v_cmp_lt_f32_e64 s[10:11], 0, v160
	s_nop 1
	v_cndmask_b32_e64 v153, v153, v156, s[10:11]
	v_mul_f32_e32 v155, 0x37800000, v153
	v_cndmask_b32_e32 v153, v153, v155, vcc
	v_cmp_class_f32_e32 vcc, v154, v176
	s_nop 1
	v_cndmask_b32_e32 v153, v153, v154, vcc
	v_div_scale_f32 v156, s[10:11], v153, v153, s73
	v_rcp_f32_e32 v157, v156
	v_lshl_add_u64 v[154:155], s[30:31], 0, v[158:159]
	v_div_scale_f32 v158, vcc, s73, v153, s73
	v_fma_f32 v159, -v156, v157, 1.0
	v_fmac_f32_e32 v157, v159, v157
	v_mul_f32_e32 v159, v158, v157
	v_fma_f32 v160, -v156, v159, v158
	v_fmac_f32_e32 v159, v160, v157
	v_fma_f32 v156, -v156, v159, v158
	v_div_fmas_f32 v156, v156, v157, v159
	v_div_fixup_f32 v156, v156, v153, s73
	v_pk_mul_f32 v[160:161], v[112:113], v[156:157] op_sel_hi:[1,0]
	v_pk_mul_f32 v[164:165], v[110:111], v[156:157] op_sel_hi:[1,0]
	v_pk_mul_f32 v[158:159], v[108:109], v[156:157] op_sel_hi:[1,0]
	v_pk_mul_f32 v[162:163], v[106:107], v[156:157] op_sel_hi:[1,0]
	s_mov_b64 s[10:11], -1
	s_cbranch_scc1 .LBB0_1386
	global_load_dwordx4 v[180:183], v[154:155], off
	global_load_dwordx4 v[184:187], v[154:155], off offset:16
	global_load_dwordx4 v[188:191], v[154:155], off offset:32
	global_load_dwordx4 v[192:195], v[154:155], off offset:48
	v_and_b32_e32 v179, 64, v177
	v_xor_b32_e32 v157, 16, v177
	v_add_u32_e32 v179, 64, v179
	v_ashrrev_i32_e32 v153, 31, v152
	v_cmp_lt_i32_e32 vcc, v157, v179
	v_lshlrev_b64 v[196:197], 12, v[152:153]
	v_lshl_add_u64 v[196:197], v[196:197], 0, v[138:139]
	v_cndmask_b32_e32 v153, v177, v157, vcc
	v_lshlrev_b32_e32 v153, 2, v153
	ds_bpermute_b32 v157, v153, v164
	ds_bpermute_b32 v179, v153, v165
	ds_bpermute_b32 v199, v153, v160
	ds_bpermute_b32 v202, v153, v161
	ds_bpermute_b32 v204, v153, v162
	ds_bpermute_b32 v205, v153, v163
	ds_bpermute_b32 v206, v153, v158
	ds_bpermute_b32 v153, v153, v159
	v_mad_u64_u32 v[200:201], s[10:11], v196, s49, v[144:145]
	v_mad_i32_i24 v201, v197, s49, v201
	s_waitcnt lgkmcnt(0)
	v_cndmask_b32_e64 v197, v179, -v179, s[4:5]
	v_cndmask_b32_e64 v196, v157, -v157, s[4:5]
	v_cndmask_b32_e64 v203, v202, -v202, s[4:5]
	v_cndmask_b32_e64 v202, v199, -v199, s[4:5]
	v_cndmask_b32_e64 v205, v205, -v205, s[4:5]
	v_cndmask_b32_e64 v204, v204, -v204, s[4:5]
	v_cndmask_b32_e64 v207, v153, -v153, s[4:5]
	v_cndmask_b32_e64 v206, v206, -v206, s[4:5]
	s_mov_b64 s[10:11], 0
	s_waitcnt vmcnt(3)
	v_mov_b32_e32 v209, v182
	v_mov_b32_e32 v182, v181
	s_waitcnt vmcnt(2)
	v_mov_b32_e32 v181, v186
	v_mov_b32_e32 v186, v185
	s_waitcnt vmcnt(1)
	v_mov_b32_e32 v185, v190
	v_mov_b32_e32 v190, v189
	s_waitcnt vmcnt(0)
	v_mov_b32_e32 v189, v194
	v_mov_b32_e32 v194, v193
	v_mov_b32_e32 v208, v180
	v_mov_b32_e32 v180, v184
	v_mov_b32_e32 v184, v188
	v_mov_b32_e32 v188, v192
	v_pk_mul_f32 v[182:183], v[196:197], v[182:183]
	v_pk_mul_f32 v[186:187], v[202:203], v[186:187]
	v_pk_mul_f32 v[190:191], v[204:205], v[190:191]
	v_pk_mul_f32 v[192:193], v[206:207], v[194:195]
	v_pk_fma_f32 v[182:183], v[164:165], v[208:209], v[182:183]
	v_pk_fma_f32 v[186:187], v[160:161], v[180:181], v[186:187]
	v_pk_fma_f32 v[184:185], v[162:163], v[184:185], v[190:191]
	v_pk_fma_f32 v[188:189], v[158:159], v[188:189], v[192:193]
	v_cvt_pk_bf16_f32 v180, v182, v183
	v_cvt_pk_bf16_f32 v181, v186, v187
	v_cvt_pk_bf16_f32 v182, v184, v185
	v_cvt_pk_bf16_f32 v183, v188, v189
	global_store_dwordx4 v[200:201], v[180:183], off offset:128

.LBB0_1392:
	v_or_b32_e32 v150, 48, v150
	v_cmp_lt_i32_e32 vcc, s70, v150
	s_and_saveexec_b64 s[10:11], vcc
	s_xor_b64 s[10:11], exec, s[10:11]
	s_add_i32 s3, s2, 0xffffc000
	s_lshr_b32 s3, s3, 8
	v_or_b32_sdwa v138, v150, s66 dst_sel:DWORD dst_unused:UNUSED_PAD src0_sel:BYTE_0 src1_sel:DWORD
	v_mov_b32_e32 v152, s3
	s_andn2_saveexec_b64 s[10:11], s[10:11]
	s_ashr_i32 s3, s2, 12
	v_and_b32_e32 v138, 0xfff, v150
	v_mov_b32_e32 v152, s3
	s_or_b64 exec, exec, s[10:11]
	v_ashrrev_i32_e32 v151, 31, v150
	s_and_b64 vcc, exec, s[8:9]
	v_lshlrev_b64 v[150:151], 4, v[150:151]
	s_cbranch_vccnz .LBB0_1398
	v_and_b32_e32 v246, 0xff0, v150
	v_lshl_add_u64 v[154:155], s[28:29], 0, v[150:151]
	v_add_u32_e32 v246, v247, v246
	ds_read_b128 v[154:157], v246
	s_lshl_b32 s3, s38, 8
	s_or_b32 s3, s3, s63
	s_ashr_i32 s3, s3, 6
	v_lshl_add_u32 v153, v152, 3, s3
	v_mad_i64_i32 v[158:159], s[10:11], v153, s72, v[138:139]
	v_or_b32_e32 v153, 2, v153
	v_mad_i64_i32 v[160:161], s[10:11], v153, s72, v[138:139]
	v_mad_u64_u32 v[162:163], s[10:11], v158, s49, v[140:141]
	v_mad_i32_i24 v163, v159, s49, v163
	s_waitcnt lgkmcnt(0)
	v_mov_b32_e32 v164, v155
	v_mov_b32_e32 v165, v156
	v_mov_b32_e32 v155, v157
	v_pk_add_f32 v[154:155], v[164:165], v[154:155]
	v_mad_u64_u32 v[164:165], s[10:11], v160, s49, v[140:141]
	v_add_f32_e32 v153, v154, v155
	v_fmamk_f32 v153, v153, 0x3c000000, v175
	v_mul_f32_e32 v154, 0x4f800000, v153
	v_cmp_gt_f32_e32 vcc, s71, v153
	v_mad_i32_i24 v165, v161, s49, v165
	s_nop 0
	v_cndmask_b32_e32 v153, v153, v154, vcc
	v_sqrt_f32_e32 v154, v153
	s_nop 0
	v_add_u32_e32 v155, -1, v154
	v_add_u32_e32 v156, 1, v154
	v_fma_f32 v157, -v155, v154, v153
	v_fma_f32 v158, -v156, v154, v153
	v_cmp_ge_f32_e64 s[10:11], 0, v157
	s_nop 1
	v_cndmask_b32_e64 v154, v154, v155, s[10:11]
	v_cmp_lt_f32_e64 s[10:11], 0, v158
	s_nop 1
	v_cndmask_b32_e64 v154, v154, v156, s[10:11]
	v_mul_f32_e32 v155, 0x37800000, v154
	v_cndmask_b32_e32 v154, v154, v155, vcc
	v_cmp_class_f32_e32 vcc, v153, v176
	s_nop 1
	v_cndmask_b32_e32 v153, v154, v153, vcc
	v_div_scale_f32 v154, s[10:11], v153, v153, 1.0
	v_rcp_f32_e32 v155, v154
	v_div_scale_f32 v156, vcc, 1.0, v153, 1.0
	v_fma_f32 v157, -v154, v155, 1.0
	v_fmac_f32_e32 v155, v157, v155
	v_mul_f32_e32 v157, v156, v155
	v_fma_f32 v158, -v154, v157, v156
	v_fmac_f32_e32 v157, v158, v155
	v_fma_f32 v154, -v154, v157, v156
	v_div_fmas_f32 v154, v154, v155, v157
	v_div_fixup_f32 v154, v154, v153, 1.0
	v_pk_mul_f32 v[156:157], v[104:105], v[154:155] op_sel_hi:[1,0]
	v_pk_mul_f32 v[158:159], v[102:103], v[154:155] op_sel_hi:[1,0]
	v_pk_mul_f32 v[160:161], v[100:101], v[154:155] op_sel_hi:[1,0]
	v_pk_mul_f32 v[180:181], v[98:99], v[154:155] op_sel_hi:[1,0]
	v_pk_mul_f32 v[182:183], v[40:41], v[154:155] op_sel_hi:[1,0]
	v_pk_mul_f32 v[184:185], v[38:39], v[154:155] op_sel_hi:[1,0]
	v_pk_mul_f32 v[186:187], v[36:37], v[154:155] op_sel_hi:[1,0]
	v_pk_mul_f32 v[188:189], v[34:35], v[154:155] op_sel_hi:[1,0]
	v_cvt_pk_bf16_f32 v154, v158, v159
	v_cvt_pk_bf16_f32 v155, v156, v157
	v_cvt_pk_bf16_f32 v156, v180, v181
	v_cvt_pk_bf16_f32 v157, v160, v161
	v_cvt_pk_bf16_f32 v158, v184, v185
	v_cvt_pk_bf16_f32 v159, v182, v183
	v_cvt_pk_bf16_f32 v160, v188, v189
	v_cvt_pk_bf16_f32 v161, v186, v187
	global_store_dwordx4 v[162:163], v[154:157], off
	global_store_dwordx4 v[164:165], v[158:161], off
	s_cbranch_execz .LBB0_1399
	s_branch .LBB0_1407
.LBB0_1398:
.LBB0_1399:
	v_and_b32_e32 v246, 0xff0, v150
	v_lshl_add_u64 v[150:151], s[34:35], 0, v[150:151]
	v_add_u32_e32 v246, v247, v246
	ds_read_b128 v[154:157], v246
	v_lshlrev_b32_e32 v164, 3, v152
	v_lshrrev_b32_e32 v150, 6, v138
	v_and_b32_e32 v151, 63, v138
	v_cndmask_b32_e64 v151, v151, v150, s[0:1]
	v_mov_b32_e32 v153, v139
	s_cmp_gt_i32 s38, 1
	v_or_b32_e32 v150, s60, v164
	s_cselect_b64 s[50:51], -1, 0
	s_cmp_lt_i32 s38, 2
	s_waitcnt lgkmcnt(0)
	v_mov_b32_e32 v158, v155
	v_mov_b32_e32 v159, v156
	v_mov_b32_e32 v155, v157
	v_pk_add_f32 v[154:155], v[158:159], v[154:155]
	s_nop 0
	v_add_f32_e32 v152, v154, v155
	v_fmamk_f32 v152, v152, 0x3b800000, v175
	v_mul_f32_e32 v154, 0x4f800000, v152
	v_cmp_gt_f32_e32 vcc, s71, v152
	s_nop 1
	v_cndmask_b32_e32 v154, v152, v154, vcc
	v_sqrt_f32_e32 v155, v154
	v_lshlrev_b32_e32 v152, 6, v151
	v_lshl_add_u64 v[152:153], s[30:31], 0, v[152:153]
	v_add_u32_e32 v151, -1, v155
	v_add_u32_e32 v156, 1, v155
	v_fma_f32 v157, -v151, v155, v154
	v_fma_f32 v158, -v156, v155, v154
	v_cmp_ge_f32_e64 s[10:11], 0, v157
	s_nop 1
	v_cndmask_b32_e64 v151, v155, v151, s[10:11]
	v_cmp_lt_f32_e64 s[10:11], 0, v158
	s_nop 1
	v_cndmask_b32_e64 v151, v151, v156, s[10:11]
	v_mul_f32_e32 v155, 0x37800000, v151
	v_cndmask_b32_e32 v151, v151, v155, vcc
	v_cmp_class_f32_e32 vcc, v154, v176
	s_nop 1
	v_cndmask_b32_e32 v151, v151, v154, vcc
	v_div_scale_f32 v154, s[10:11], v151, v151, s73
	v_rcp_f32_e32 v155, v154
	v_div_scale_f32 v156, vcc, s73, v151, s73
	s_mov_b64 s[10:11], -1
	v_fma_f32 v157, -v154, v155, 1.0
	v_fmac_f32_e32 v155, v157, v155
	v_mul_f32_e32 v157, v156, v155
	v_fma_f32 v158, -v154, v157, v156
	v_fmac_f32_e32 v157, v158, v155
	v_fma_f32 v154, -v154, v157, v156
	v_div_fmas_f32 v154, v154, v155, v157
	v_div_fixup_f32 v154, v154, v151, s73
	v_pk_mul_f32 v[158:159], v[104:105], v[154:155] op_sel_hi:[1,0]
	v_pk_mul_f32 v[162:163], v[102:103], v[154:155] op_sel_hi:[1,0]
	v_pk_mul_f32 v[156:157], v[100:101], v[154:155] op_sel_hi:[1,0]
	v_pk_mul_f32 v[160:161], v[98:99], v[154:155] op_sel_hi:[1,0]
	s_cbranch_scc1 .LBB0_1401
	global_load_dwordx4 v[180:183], v[152:153], off
	global_load_dwordx4 v[184:187], v[152:153], off offset:16
	global_load_dwordx4 v[188:191], v[152:153], off offset:32
	global_load_dwordx4 v[192:195], v[152:153], off offset:48
	v_and_b32_e32 v165, 64, v177
	v_xor_b32_e32 v155, 16, v177
	v_add_u32_e32 v165, 64, v165
	v_ashrrev_i32_e32 v151, 31, v150
	v_cmp_lt_i32_e32 vcc, v155, v165
	v_lshlrev_b64 v[196:197], 12, v[150:151]
	v_lshl_add_u64 v[196:197], v[196:197], 0, v[138:139]
	v_cndmask_b32_e32 v151, v177, v155, vcc
	v_lshlrev_b32_e32 v151, 2, v151
	ds_bpermute_b32 v155, v151, v162
	ds_bpermute_b32 v165, v151, v163
	ds_bpermute_b32 v179, v151, v158
	ds_bpermute_b32 v199, v151, v159
	ds_bpermute_b32 v204, v151, v160
	ds_bpermute_b32 v205, v151, v161
	ds_bpermute_b32 v206, v151, v156
	ds_bpermute_b32 v151, v151, v157
	v_mad_u64_u32 v[200:201], s[10:11], v196, s49, v[144:145]
	v_mad_i32_i24 v201, v197, s49, v201
	s_waitcnt lgkmcnt(0)
	v_cndmask_b32_e64 v197, v165, -v165, s[4:5]
	v_cndmask_b32_e64 v196, v155, -v155, s[4:5]
	v_cndmask_b32_e64 v203, v199, -v199, s[4:5]
	v_cndmask_b32_e64 v202, v179, -v179, s[4:5]
	v_cndmask_b32_e64 v205, v205, -v205, s[4:5]
	v_cndmask_b32_e64 v204, v204, -v204, s[4:5]
	v_cndmask_b32_e64 v207, v151, -v151, s[4:5]
	v_cndmask_b32_e64 v206, v206, -v206, s[4:5]
	s_mov_b64 s[10:11], 0
	s_waitcnt vmcnt(3)
	v_mov_b32_e32 v209, v182
	v_mov_b32_e32 v182, v181
	s_waitcnt vmcnt(2)
	v_mov_b32_e32 v181, v186
	v_mov_b32_e32 v186, v185
	s_waitcnt vmcnt(1)
	v_mov_b32_e32 v185, v190
	v_mov_b32_e32 v190, v189
	s_waitcnt vmcnt(0)
	v_mov_b32_e32 v189, v194
	v_mov_b32_e32 v194, v193
	v_mov_b32_e32 v208, v180
	v_mov_b32_e32 v180, v184
	v_mov_b32_e32 v184, v188
	v_mov_b32_e32 v188, v192
	v_pk_mul_f32 v[182:183], v[196:197], v[182:183]
	v_pk_mul_f32 v[186:187], v[202:203], v[186:187]
	v_pk_mul_f32 v[190:191], v[204:205], v[190:191]
	v_pk_mul_f32 v[192:193], v[206:207], v[194:195]
	v_pk_fma_f32 v[182:183], v[162:163], v[208:209], v[182:183]
	v_pk_fma_f32 v[186:187], v[158:159], v[180:181], v[186:187]
	v_pk_fma_f32 v[184:185], v[160:161], v[184:185], v[190:191]
	v_pk_fma_f32 v[188:189], v[156:157], v[188:189], v[192:193]
	v_cvt_pk_bf16_f32 v180, v182, v183
	v_cvt_pk_bf16_f32 v181, v186, v187
	v_cvt_pk_bf16_f32 v182, v184, v185
	v_cvt_pk_bf16_f32 v183, v188, v189
	global_store_dwordx4 v[200:201], v[180:183], off offset:128

.LBB0_1407:
	s_addk_i32 s2, 0x80
	s_nop 0
	v_or_b32_e32 v150, s2, v1
	v_cmp_lt_i32_e32 vcc, s70, v150
	s_and_saveexec_b64 s[10:11], vcc
	s_xor_b64 s[10:11], exec, s[10:11]
	s_add_i32 s3, s2, 0xffffc000
	s_lshr_b32 s3, s3, 8
	v_and_b32_e32 v138, 0xcf, v150
	v_or_b32_e32 v138, 0x1000, v138
	v_mov_b32_e32 v154, s3
	s_andn2_saveexec_b64 s[10:11], s[10:11]
	s_ashr_i32 s3, s2, 12
	v_and_b32_e32 v138, 0xfcf, v150
	v_mov_b32_e32 v154, s3
	s_or_b64 exec, exec, s[10:11]
	v_ashrrev_i32_e32 v151, 31, v150
	s_and_b64 vcc, exec, s[8:9]
	v_lshlrev_b64 v[152:153], 4, v[150:151]
	s_cbranch_vccnz .LBB0_1413
	v_and_b32_e32 v246, 0xff0, v152
	v_lshl_add_u64 v[156:157], s[28:29], 0, v[152:153]
	v_add_u32_e32 v246, v247, v246
	ds_read_b128 v[156:159], v246
	s_lshl_b32 s3, s38, 8
	s_or_b32 s3, s3, s63
	s_ashr_i32 s3, s3, 6
	v_lshl_add_u32 v151, v154, 3, s3
	v_mad_i64_i32 v[160:161], s[10:11], v151, s72, v[138:139]
	v_or_b32_e32 v151, 2, v151
	v_mad_i64_i32 v[162:163], s[10:11], v151, s72, v[138:139]
	v_mad_u64_u32 v[164:165], s[10:11], v160, s49, v[140:141]
	v_mad_i32_i24 v165, v161, s49, v165
	s_waitcnt lgkmcnt(0)
	v_mov_b32_e32 v180, v157
	v_mov_b32_e32 v181, v158
	v_mov_b32_e32 v157, v159
	v_pk_add_f32 v[156:157], v[180:181], v[156:157]
	v_mad_u64_u32 v[180:181], s[10:11], v162, s49, v[140:141]
	v_add_f32_e32 v151, v156, v157
	v_fmamk_f32 v151, v151, 0x3c000000, v175
	v_mul_f32_e32 v155, 0x4f800000, v151
	v_cmp_gt_f32_e32 vcc, s71, v151
	v_mad_i32_i24 v181, v163, s49, v181
	s_nop 0
	v_cndmask_b32_e32 v151, v151, v155, vcc
	v_sqrt_f32_e32 v155, v151
	s_nop 0
	v_add_u32_e32 v156, -1, v155
	v_add_u32_e32 v157, 1, v155
	v_fma_f32 v158, -v156, v155, v151
	v_fma_f32 v159, -v157, v155, v151
	v_cmp_ge_f32_e64 s[10:11], 0, v158
	s_nop 1
	v_cndmask_b32_e64 v155, v155, v156, s[10:11]
	v_cmp_lt_f32_e64 s[10:11], 0, v159
	s_nop 1
	v_cndmask_b32_e64 v155, v155, v157, s[10:11]
	v_mul_f32_e32 v156, 0x37800000, v155
	v_cndmask_b32_e32 v155, v155, v156, vcc
	v_cmp_class_f32_e32 vcc, v151, v176
	s_nop 1
	v_cndmask_b32_e32 v151, v155, v151, vcc
	v_div_scale_f32 v155, s[10:11], v151, v151, 1.0
	v_rcp_f32_e32 v156, v155
	v_div_scale_f32 v157, vcc, 1.0, v151, 1.0
	v_fma_f32 v158, -v155, v156, 1.0
	v_fmac_f32_e32 v156, v158, v156
	v_mul_f32_e32 v158, v157, v156
	v_fma_f32 v159, -v155, v158, v157
	v_fmac_f32_e32 v158, v159, v156
	v_fma_f32 v155, -v155, v158, v157
	v_div_fmas_f32 v155, v155, v156, v158
	v_div_fixup_f32 v156, v155, v151, 1.0
	v_pk_mul_f32 v[158:159], v[96:97], v[156:157] op_sel_hi:[1,0]
	v_pk_mul_f32 v[160:161], v[94:95], v[156:157] op_sel_hi:[1,0]
	v_pk_mul_f32 v[162:163], v[92:93], v[156:157] op_sel_hi:[1,0]
	v_pk_mul_f32 v[182:183], v[90:91], v[156:157] op_sel_hi:[1,0]
	v_pk_mul_f32 v[184:185], v[32:33], v[156:157] op_sel_hi:[1,0]
	v_pk_mul_f32 v[186:187], v[30:31], v[156:157] op_sel_hi:[1,0]
	v_pk_mul_f32 v[188:189], v[28:29], v[156:157] op_sel_hi:[1,0]
	v_pk_mul_f32 v[190:191], v[26:27], v[156:157] op_sel_hi:[1,0]
	v_cvt_pk_bf16_f32 v156, v160, v161
	v_cvt_pk_bf16_f32 v157, v158, v159
	v_cvt_pk_bf16_f32 v158, v182, v183
	v_cvt_pk_bf16_f32 v159, v162, v163
	v_cvt_pk_bf16_f32 v160, v186, v187
	v_cvt_pk_bf16_f32 v161, v184, v185
	v_cvt_pk_bf16_f32 v162, v190, v191
	v_cvt_pk_bf16_f32 v163, v188, v189
	global_store_dwordx4 v[164:165], v[156:159], off
	global_store_dwordx4 v[180:181], v[160:163], off
	s_cbranch_execz .LBB0_1414
	s_branch .LBB0_1422
.LBB0_1413:
.LBB0_1414:
	v_and_b32_e32 v246, 0xff0, v152
	v_lshl_add_u64 v[152:153], s[34:35], 0, v[152:153]
	v_add_u32_e32 v246, v247, v246
	ds_read_b128 v[156:159], v246
	v_lshlrev_b32_e32 v151, 3, v154
	v_lshrrev_b32_e32 v152, 6, v138
	v_and_b32_e32 v153, 63, v138
	v_cndmask_b32_e64 v153, v153, v152, s[0:1]
	v_mov_b32_e32 v155, v139
	s_cmp_gt_i32 s38, 1
	v_or_b32_e32 v152, s60, v151
	s_cselect_b64 s[50:51], -1, 0
	s_cmp_lt_i32 s38, 2
	s_waitcnt lgkmcnt(0)
	v_mov_b32_e32 v160, v157
	v_mov_b32_e32 v161, v158
	v_mov_b32_e32 v157, v159
	v_pk_add_f32 v[156:157], v[160:161], v[156:157]
	s_nop 0
	v_add_f32_e32 v154, v156, v157
	v_fmamk_f32 v154, v154, 0x3b800000, v175
	v_mul_f32_e32 v156, 0x4f800000, v154
	v_cmp_gt_f32_e32 vcc, s71, v154
	s_nop 1
	v_cndmask_b32_e32 v156, v154, v156, vcc
	v_sqrt_f32_e32 v157, v156
	v_lshlrev_b32_e32 v154, 6, v153
	v_lshl_add_u64 v[154:155], s[30:31], 0, v[154:155]
	v_add_u32_e32 v153, -1, v157
	v_add_u32_e32 v158, 1, v157
	v_fma_f32 v159, -v153, v157, v156
	v_fma_f32 v160, -v158, v157, v156
	v_cmp_ge_f32_e64 s[10:11], 0, v159
	s_nop 1
	v_cndmask_b32_e64 v153, v157, v153, s[10:11]
	v_cmp_lt_f32_e64 s[10:11], 0, v160
	s_nop 1
	v_cndmask_b32_e64 v153, v153, v158, s[10:11]
	v_mul_f32_e32 v157, 0x37800000, v153
	v_cndmask_b32_e32 v153, v153, v157, vcc
	v_cmp_class_f32_e32 vcc, v156, v176
	s_nop 1
	v_cndmask_b32_e32 v153, v153, v156, vcc
	v_div_scale_f32 v156, s[10:11], v153, v153, s73
	v_rcp_f32_e32 v157, v156
	v_div_scale_f32 v158, vcc, s73, v153, s73
	s_mov_b64 s[10:11], -1
	v_fma_f32 v159, -v156, v157, 1.0
	v_fmac_f32_e32 v157, v159, v157
	v_mul_f32_e32 v159, v158, v157
	v_fma_f32 v160, -v156, v159, v158
	v_fmac_f32_e32 v159, v160, v157
	v_fma_f32 v156, -v156, v159, v158
	v_div_fmas_f32 v156, v156, v157, v159
	v_div_fixup_f32 v156, v156, v153, s73
	v_pk_mul_f32 v[160:161], v[96:97], v[156:157] op_sel_hi:[1,0]
	v_pk_mul_f32 v[164:165], v[94:95], v[156:157] op_sel_hi:[1,0]
	v_pk_mul_f32 v[158:159], v[92:93], v[156:157] op_sel_hi:[1,0]
	v_pk_mul_f32 v[162:163], v[90:91], v[156:157] op_sel_hi:[1,0]
	s_cbranch_scc1 .LBB0_1416
	global_load_dwordx4 v[180:183], v[154:155], off
	global_load_dwordx4 v[184:187], v[154:155], off offset:16
	global_load_dwordx4 v[188:191], v[154:155], off offset:32
	global_load_dwordx4 v[192:195], v[154:155], off offset:48
	v_and_b32_e32 v179, 64, v177
	v_xor_b32_e32 v157, 16, v177
	v_add_u32_e32 v179, 64, v179
	v_ashrrev_i32_e32 v153, 31, v152
	v_cmp_lt_i32_e32 vcc, v157, v179
	v_lshlrev_b64 v[196:197], 12, v[152:153]
	v_lshl_add_u64 v[196:197], v[196:197], 0, v[138:139]
	v_cndmask_b32_e32 v153, v177, v157, vcc
	v_lshlrev_b32_e32 v153, 2, v153
	ds_bpermute_b32 v157, v153, v164
	ds_bpermute_b32 v179, v153, v165
	ds_bpermute_b32 v199, v153, v160
	ds_bpermute_b32 v202, v153, v161
	ds_bpermute_b32 v204, v153, v162
	ds_bpermute_b32 v205, v153, v163
	ds_bpermute_b32 v206, v153, v158
	ds_bpermute_b32 v153, v153, v159
	v_mad_u64_u32 v[200:201], s[10:11], v196, s49, v[144:145]
	v_mad_i32_i24 v201, v197, s49, v201
	s_waitcnt lgkmcnt(0)
	v_cndmask_b32_e64 v197, v179, -v179, s[4:5]
	v_cndmask_b32_e64 v196, v157, -v157, s[4:5]
	v_cndmask_b32_e64 v203, v202, -v202, s[4:5]
	v_cndmask_b32_e64 v202, v199, -v199, s[4:5]
	v_cndmask_b32_e64 v205, v205, -v205, s[4:5]
	v_cndmask_b32_e64 v204, v204, -v204, s[4:5]
	v_cndmask_b32_e64 v207, v153, -v153, s[4:5]
	v_cndmask_b32_e64 v206, v206, -v206, s[4:5]
	s_mov_b64 s[10:11], 0
	s_waitcnt vmcnt(3)
	v_mov_b32_e32 v209, v182
	v_mov_b32_e32 v182, v181
	s_waitcnt vmcnt(2)
	v_mov_b32_e32 v181, v186
	v_mov_b32_e32 v186, v185
	s_waitcnt vmcnt(1)
	v_mov_b32_e32 v185, v190
	v_mov_b32_e32 v190, v189
	s_waitcnt vmcnt(0)
	v_mov_b32_e32 v189, v194
	v_mov_b32_e32 v194, v193
	v_mov_b32_e32 v208, v180
	v_mov_b32_e32 v180, v184
	v_mov_b32_e32 v184, v188
	v_mov_b32_e32 v188, v192
	v_pk_mul_f32 v[182:183], v[196:197], v[182:183]
	v_pk_mul_f32 v[186:187], v[202:203], v[186:187]
	v_pk_mul_f32 v[190:191], v[204:205], v[190:191]
	v_pk_mul_f32 v[192:193], v[206:207], v[194:195]
	v_pk_fma_f32 v[182:183], v[164:165], v[208:209], v[182:183]
	v_pk_fma_f32 v[186:187], v[160:161], v[180:181], v[186:187]
	v_pk_fma_f32 v[184:185], v[162:163], v[184:185], v[190:191]
	v_pk_fma_f32 v[188:189], v[158:159], v[188:189], v[192:193]
	v_cvt_pk_bf16_f32 v180, v182, v183
	v_cvt_pk_bf16_f32 v181, v186, v187
	v_cvt_pk_bf16_f32 v182, v184, v185
	v_cvt_pk_bf16_f32 v183, v188, v189
	global_store_dwordx4 v[200:201], v[180:183], off offset:128

.LBB0_1422:
	s_nop 1
	v_or_b32_e32 v152, 16, v150
	v_cmp_lt_i32_e32 vcc, s70, v152
	s_and_saveexec_b64 s[10:11], vcc
	s_xor_b64 s[10:11], exec, s[10:11]
	s_add_i32 s3, s2, 0xffffc000
	s_lshr_b32 s3, s3, 8
	v_and_b32_e32 v138, 0xdf, v152
	v_or_b32_e32 v138, 0x1000, v138
	v_mov_b32_e32 v151, s3
	s_andn2_saveexec_b64 s[10:11], s[10:11]
	s_ashr_i32 s3, s2, 12
	v_and_b32_e32 v138, 0xfdf, v152
	v_mov_b32_e32 v151, s3
	s_or_b64 exec, exec, s[10:11]
	v_ashrrev_i32_e32 v153, 31, v152
	s_and_b64 vcc, exec, s[8:9]
	v_lshlrev_b64 v[152:153], 4, v[152:153]
	s_cbranch_vccnz .LBB0_1428
	v_and_b32_e32 v246, 0xff0, v152
	v_lshl_add_u64 v[154:155], s[28:29], 0, v[152:153]
	v_add_u32_e32 v246, v247, v246
	ds_read_b128 v[154:157], v246
	s_lshl_b32 s3, s38, 8
	s_or_b32 s3, s3, s63
	s_ashr_i32 s3, s3, 6
	v_lshl_add_u32 v160, v151, 3, s3
	v_mad_i64_i32 v[158:159], s[10:11], v160, s72, v[138:139]
	v_or_b32_e32 v160, 2, v160
	v_mad_i64_i32 v[160:161], s[10:11], v160, s72, v[138:139]
	v_mad_u64_u32 v[162:163], s[10:11], v158, s49, v[140:141]
	v_mad_i32_i24 v163, v159, s49, v163
	s_waitcnt lgkmcnt(0)
	v_mov_b32_e32 v164, v155
	v_mov_b32_e32 v165, v156
	v_mov_b32_e32 v155, v157
	v_pk_add_f32 v[154:155], v[164:165], v[154:155]
	v_mad_u64_u32 v[164:165], s[10:11], v160, s49, v[140:141]
	v_add_f32_e32 v154, v154, v155
	v_fmamk_f32 v154, v154, 0x3c000000, v175
	v_mul_f32_e32 v155, 0x4f800000, v154
	v_cmp_gt_f32_e32 vcc, s71, v154
	v_mad_i32_i24 v165, v161, s49, v165
	s_nop 0
	v_cndmask_b32_e32 v154, v154, v155, vcc
	v_sqrt_f32_e32 v155, v154
	s_nop 0
	v_add_u32_e32 v156, -1, v155
	v_add_u32_e32 v157, 1, v155
	v_fma_f32 v158, -v156, v155, v154
	v_fma_f32 v159, -v157, v155, v154
	v_cmp_ge_f32_e64 s[10:11], 0, v158
	s_nop 1
	v_cndmask_b32_e64 v155, v155, v156, s[10:11]
	v_cmp_lt_f32_e64 s[10:11], 0, v159
	s_nop 1
	v_cndmask_b32_e64 v155, v155, v157, s[10:11]
	v_mul_f32_e32 v156, 0x37800000, v155
	v_cndmask_b32_e32 v155, v155, v156, vcc
	v_cmp_class_f32_e32 vcc, v154, v176
	s_nop 1
	v_cndmask_b32_e32 v154, v155, v154, vcc
	v_div_scale_f32 v155, s[10:11], v154, v154, 1.0
	v_rcp_f32_e32 v156, v155
	v_div_scale_f32 v157, vcc, 1.0, v154, 1.0
	v_fma_f32 v158, -v155, v156, 1.0
	v_fmac_f32_e32 v156, v158, v156
	v_mul_f32_e32 v158, v157, v156
	v_fma_f32 v159, -v155, v158, v157
	v_fmac_f32_e32 v158, v159, v156
	v_fma_f32 v155, -v155, v158, v157
	v_div_fmas_f32 v155, v155, v156, v158
	v_div_fixup_f32 v154, v155, v154, 1.0
	v_pk_mul_f32 v[156:157], v[88:89], v[154:155] op_sel_hi:[1,0]
	v_pk_mul_f32 v[158:159], v[86:87], v[154:155] op_sel_hi:[1,0]
	v_pk_mul_f32 v[160:161], v[84:85], v[154:155] op_sel_hi:[1,0]
	v_pk_mul_f32 v[180:181], v[82:83], v[154:155] op_sel_hi:[1,0]
	v_pk_mul_f32 v[182:183], v[24:25], v[154:155] op_sel_hi:[1,0]
	v_pk_mul_f32 v[184:185], v[22:23], v[154:155] op_sel_hi:[1,0]
	v_pk_mul_f32 v[186:187], v[20:21], v[154:155] op_sel_hi:[1,0]
	v_pk_mul_f32 v[188:189], v[18:19], v[154:155] op_sel_hi:[1,0]
	v_cvt_pk_bf16_f32 v154, v158, v159
	v_cvt_pk_bf16_f32 v155, v156, v157
	v_cvt_pk_bf16_f32 v156, v180, v181
	v_cvt_pk_bf16_f32 v157, v160, v161
	v_cvt_pk_bf16_f32 v158, v184, v185
	v_cvt_pk_bf16_f32 v159, v182, v183
	v_cvt_pk_bf16_f32 v160, v188, v189
	v_cvt_pk_bf16_f32 v161, v186, v187
	global_store_dwordx4 v[162:163], v[154:157], off
	global_store_dwordx4 v[164:165], v[158:161], off
	s_cbranch_execz .LBB0_1429
	s_branch .LBB0_1437
.LBB0_1428:
.LBB0_1429:
	v_and_b32_e32 v246, 0xff0, v152
	v_lshl_add_u64 v[152:153], s[34:35], 0, v[152:153]
	v_add_u32_e32 v246, v247, v246
	ds_read_b128 v[154:157], v246
	v_lshrrev_b32_e32 v152, 6, v138
	v_and_b32_e32 v153, 63, v138
	v_cndmask_b32_e64 v153, v153, v152, s[0:1]
	v_lshlrev_b32_e32 v158, 6, v153
	v_mov_b32_e32 v159, v139
	v_lshlrev_b32_e32 v151, 3, v151
	s_cmp_gt_i32 s38, 1
	v_or_b32_e32 v152, s60, v151
	s_cselect_b64 s[50:51], -1, 0
	s_cmp_lt_i32 s38, 2
	s_waitcnt lgkmcnt(0)
	v_mov_b32_e32 v160, v155
	v_mov_b32_e32 v161, v156
	v_mov_b32_e32 v155, v157
	v_pk_add_f32 v[154:155], v[160:161], v[154:155]
	s_nop 0
	v_add_f32_e32 v154, v154, v155
	v_fmamk_f32 v154, v154, 0x3b800000, v175
	v_mul_f32_e32 v155, 0x4f800000, v154
	v_cmp_gt_f32_e32 vcc, s71, v154
	s_nop 1
	v_cndmask_b32_e32 v154, v154, v155, vcc
	v_sqrt_f32_e32 v155, v154
	s_nop 0
	v_add_u32_e32 v153, -1, v155
	v_add_u32_e32 v156, 1, v155
	v_fma_f32 v157, -v153, v155, v154
	v_fma_f32 v160, -v156, v155, v154
	v_cmp_ge_f32_e64 s[10:11], 0, v157
	s_nop 1
	v_cndmask_b32_e64 v153, v155, v153, s[10:11]
	v_cmp_lt_f32_e64 s[10:11], 0, v160
	s_nop 1
	v_cndmask_b32_e64 v153, v153, v156, s[10:11]
	v_mul_f32_e32 v155, 0x37800000, v153
	v_cndmask_b32_e32 v153, v153, v155, vcc
	v_cmp_class_f32_e32 vcc, v154, v176
	s_nop 1
	v_cndmask_b32_e32 v153, v153, v154, vcc
	v_div_scale_f32 v156, s[10:11], v153, v153, s73
	v_rcp_f32_e32 v157, v156
	v_lshl_add_u64 v[154:155], s[30:31], 0, v[158:159]
	v_div_scale_f32 v158, vcc, s73, v153, s73
	v_fma_f32 v159, -v156, v157, 1.0
	v_fmac_f32_e32 v157, v159, v157
	v_mul_f32_e32 v159, v158, v157
	v_fma_f32 v160, -v156, v159, v158
	v_fmac_f32_e32 v159, v160, v157
	v_fma_f32 v156, -v156, v159, v158
	v_div_fmas_f32 v156, v156, v157, v159
	v_div_fixup_f32 v156, v156, v153, s73
	v_pk_mul_f32 v[160:161], v[88:89], v[156:157] op_sel_hi:[1,0]
	v_pk_mul_f32 v[164:165], v[86:87], v[156:157] op_sel_hi:[1,0]
	v_pk_mul_f32 v[158:159], v[84:85], v[156:157] op_sel_hi:[1,0]
	v_pk_mul_f32 v[162:163], v[82:83], v[156:157] op_sel_hi:[1,0]
	s_mov_b64 s[10:11], -1
	s_cbranch_scc1 .LBB0_1431
	global_load_dwordx4 v[180:183], v[154:155], off
	global_load_dwordx4 v[184:187], v[154:155], off offset:16
	global_load_dwordx4 v[188:191], v[154:155], off offset:32
	global_load_dwordx4 v[192:195], v[154:155], off offset:48
	v_and_b32_e32 v179, 64, v177
	v_xor_b32_e32 v157, 16, v177
	v_add_u32_e32 v179, 64, v179
	v_ashrrev_i32_e32 v153, 31, v152
	v_cmp_lt_i32_e32 vcc, v157, v179
	v_lshlrev_b64 v[196:197], 12, v[152:153]
	v_lshl_add_u64 v[196:197], v[196:197], 0, v[138:139]
	v_cndmask_b32_e32 v153, v177, v157, vcc
	v_lshlrev_b32_e32 v153, 2, v153
	ds_bpermute_b32 v157, v153, v164
	ds_bpermute_b32 v179, v153, v165
	ds_bpermute_b32 v199, v153, v160
	ds_bpermute_b32 v202, v153, v161
	ds_bpermute_b32 v204, v153, v162
	ds_bpermute_b32 v205, v153, v163
	ds_bpermute_b32 v206, v153, v158
	ds_bpermute_b32 v153, v153, v159
	v_mad_u64_u32 v[200:201], s[10:11], v196, s49, v[144:145]
	v_mad_i32_i24 v201, v197, s49, v201
	s_waitcnt lgkmcnt(0)
	v_cndmask_b32_e64 v197, v179, -v179, s[4:5]
	v_cndmask_b32_e64 v196, v157, -v157, s[4:5]
	v_cndmask_b32_e64 v203, v202, -v202, s[4:5]
	v_cndmask_b32_e64 v202, v199, -v199, s[4:5]
	v_cndmask_b32_e64 v205, v205, -v205, s[4:5]
	v_cndmask_b32_e64 v204, v204, -v204, s[4:5]
	v_cndmask_b32_e64 v207, v153, -v153, s[4:5]
	v_cndmask_b32_e64 v206, v206, -v206, s[4:5]
	s_mov_b64 s[10:11], 0
	s_waitcnt vmcnt(3)
	v_mov_b32_e32 v209, v182
	v_mov_b32_e32 v182, v181
	s_waitcnt vmcnt(2)
	v_mov_b32_e32 v181, v186
	v_mov_b32_e32 v186, v185
	s_waitcnt vmcnt(1)
	v_mov_b32_e32 v185, v190
	v_mov_b32_e32 v190, v189
	s_waitcnt vmcnt(0)
	v_mov_b32_e32 v189, v194
	v_mov_b32_e32 v194, v193
	v_mov_b32_e32 v208, v180
	v_mov_b32_e32 v180, v184
	v_mov_b32_e32 v184, v188
	v_mov_b32_e32 v188, v192
	v_pk_mul_f32 v[182:183], v[196:197], v[182:183]
	v_pk_mul_f32 v[186:187], v[202:203], v[186:187]
	v_pk_mul_f32 v[190:191], v[204:205], v[190:191]
	v_pk_mul_f32 v[192:193], v[206:207], v[194:195]
	v_pk_fma_f32 v[182:183], v[164:165], v[208:209], v[182:183]
	v_pk_fma_f32 v[186:187], v[160:161], v[180:181], v[186:187]
	v_pk_fma_f32 v[184:185], v[162:163], v[184:185], v[190:191]
	v_pk_fma_f32 v[188:189], v[158:159], v[188:189], v[192:193]
	v_cvt_pk_bf16_f32 v180, v182, v183
	v_cvt_pk_bf16_f32 v181, v186, v187
	v_cvt_pk_bf16_f32 v182, v184, v185
	v_cvt_pk_bf16_f32 v183, v188, v189
	global_store_dwordx4 v[200:201], v[180:183], off offset:128

.LBB0_1437:
	s_nop 1
	v_or_b32_e32 v152, 32, v150
	v_cmp_lt_i32_e32 vcc, s70, v152
	s_and_saveexec_b64 s[10:11], vcc
	s_xor_b64 s[10:11], exec, s[10:11]
	s_add_i32 s3, s2, 0xffffc000
	s_lshr_b32 s3, s3, 8
	v_and_b32_e32 v138, 0xef, v152
	v_or_b32_e32 v138, 0x1000, v138
	v_mov_b32_e32 v151, s3
	s_andn2_saveexec_b64 s[10:11], s[10:11]
	s_ashr_i32 s3, s2, 12
	v_and_b32_e32 v138, 0xfef, v152
	v_mov_b32_e32 v151, s3
	s_or_b64 exec, exec, s[10:11]
	v_ashrrev_i32_e32 v153, 31, v152
	s_and_b64 vcc, exec, s[8:9]
	v_lshlrev_b64 v[152:153], 4, v[152:153]
	s_cbranch_vccnz .LBB0_1443
	v_and_b32_e32 v246, 0xff0, v152
	v_lshl_add_u64 v[154:155], s[28:29], 0, v[152:153]
	v_add_u32_e32 v246, v247, v246
	ds_read_b128 v[154:157], v246
	s_lshl_b32 s3, s38, 8
	s_or_b32 s3, s3, s63
	s_ashr_i32 s3, s3, 6
	v_lshl_add_u32 v160, v151, 3, s3
	v_mad_i64_i32 v[158:159], s[10:11], v160, s72, v[138:139]
	v_or_b32_e32 v160, 2, v160
	v_mad_i64_i32 v[160:161], s[10:11], v160, s72, v[138:139]
	v_mad_u64_u32 v[162:163], s[10:11], v158, s49, v[140:141]
	v_mad_i32_i24 v163, v159, s49, v163
	s_waitcnt lgkmcnt(0)
	v_mov_b32_e32 v164, v155
	v_mov_b32_e32 v165, v156
	v_mov_b32_e32 v155, v157
	v_pk_add_f32 v[154:155], v[164:165], v[154:155]
	v_mad_u64_u32 v[164:165], s[10:11], v160, s49, v[140:141]
	v_add_f32_e32 v154, v154, v155
	v_fmamk_f32 v154, v154, 0x3c000000, v175
	v_mul_f32_e32 v155, 0x4f800000, v154
	v_cmp_gt_f32_e32 vcc, s71, v154
	v_mad_i32_i24 v165, v161, s49, v165
	s_nop 0
	v_cndmask_b32_e32 v154, v154, v155, vcc
	v_sqrt_f32_e32 v155, v154
	s_nop 0
	v_add_u32_e32 v156, -1, v155
	v_add_u32_e32 v157, 1, v155
	v_fma_f32 v158, -v156, v155, v154
	v_fma_f32 v159, -v157, v155, v154
	v_cmp_ge_f32_e64 s[10:11], 0, v158
	s_nop 1
	v_cndmask_b32_e64 v155, v155, v156, s[10:11]
	v_cmp_lt_f32_e64 s[10:11], 0, v159
	s_nop 1
	v_cndmask_b32_e64 v155, v155, v157, s[10:11]
	v_mul_f32_e32 v156, 0x37800000, v155
	v_cndmask_b32_e32 v155, v155, v156, vcc
	v_cmp_class_f32_e32 vcc, v154, v176
	s_nop 1
	v_cndmask_b32_e32 v154, v155, v154, vcc
	v_div_scale_f32 v155, s[10:11], v154, v154, 1.0
	v_rcp_f32_e32 v156, v155
	v_div_scale_f32 v157, vcc, 1.0, v154, 1.0
	v_fma_f32 v158, -v155, v156, 1.0
	v_fmac_f32_e32 v156, v158, v156
	v_mul_f32_e32 v158, v157, v156
	v_fma_f32 v159, -v155, v158, v157
	v_fmac_f32_e32 v158, v159, v156
	v_fma_f32 v155, -v155, v158, v157
	v_div_fmas_f32 v155, v155, v156, v158
	v_div_fixup_f32 v154, v155, v154, 1.0
	v_pk_mul_f32 v[156:157], v[80:81], v[154:155] op_sel_hi:[1,0]
	v_pk_mul_f32 v[158:159], v[78:79], v[154:155] op_sel_hi:[1,0]
	v_pk_mul_f32 v[160:161], v[76:77], v[154:155] op_sel_hi:[1,0]
	v_pk_mul_f32 v[180:181], v[74:75], v[154:155] op_sel_hi:[1,0]
	v_pk_mul_f32 v[182:183], v[16:17], v[154:155] op_sel_hi:[1,0]
	v_pk_mul_f32 v[184:185], v[14:15], v[154:155] op_sel_hi:[1,0]
	v_pk_mul_f32 v[186:187], v[12:13], v[154:155] op_sel_hi:[1,0]
	v_pk_mul_f32 v[188:189], v[10:11], v[154:155] op_sel_hi:[1,0]
	v_cvt_pk_bf16_f32 v154, v158, v159
	v_cvt_pk_bf16_f32 v155, v156, v157
	v_cvt_pk_bf16_f32 v156, v180, v181
	v_cvt_pk_bf16_f32 v157, v160, v161
	v_cvt_pk_bf16_f32 v158, v184, v185
	v_cvt_pk_bf16_f32 v159, v182, v183
	v_cvt_pk_bf16_f32 v160, v188, v189
	v_cvt_pk_bf16_f32 v161, v186, v187
	global_store_dwordx4 v[162:163], v[154:157], off
	global_store_dwordx4 v[164:165], v[158:161], off
	s_cbranch_execz .LBB0_1444
	s_branch .LBB0_1452
.LBB0_1443:
.LBB0_1444:
	v_and_b32_e32 v246, 0xff0, v152
	v_lshl_add_u64 v[152:153], s[34:35], 0, v[152:153]
	v_add_u32_e32 v246, v247, v246
	ds_read_b128 v[154:157], v246
	v_lshrrev_b32_e32 v152, 6, v138
	v_and_b32_e32 v153, 63, v138
	v_cndmask_b32_e64 v153, v153, v152, s[0:1]
	v_lshlrev_b32_e32 v158, 6, v153
	v_mov_b32_e32 v159, v139
	v_lshlrev_b32_e32 v151, 3, v151
	s_cmp_gt_i32 s38, 1
	v_or_b32_e32 v152, s60, v151
	s_cselect_b64 s[50:51], -1, 0
	s_cmp_lt_i32 s38, 2
	s_waitcnt lgkmcnt(0)
	v_mov_b32_e32 v160, v155
	v_mov_b32_e32 v161, v156
	v_mov_b32_e32 v155, v157
	v_pk_add_f32 v[154:155], v[160:161], v[154:155]
	s_nop 0
	v_add_f32_e32 v154, v154, v155
	v_fmamk_f32 v154, v154, 0x3b800000, v175
	v_mul_f32_e32 v155, 0x4f800000, v154
	v_cmp_gt_f32_e32 vcc, s71, v154
	s_nop 1
	v_cndmask_b32_e32 v154, v154, v155, vcc
	v_sqrt_f32_e32 v155, v154
	s_nop 0
	v_add_u32_e32 v153, -1, v155
	v_add_u32_e32 v156, 1, v155
	v_fma_f32 v157, -v153, v155, v154
	v_fma_f32 v160, -v156, v155, v154
	v_cmp_ge_f32_e64 s[10:11], 0, v157
	s_nop 1
	v_cndmask_b32_e64 v153, v155, v153, s[10:11]
	v_cmp_lt_f32_e64 s[10:11], 0, v160
	s_nop 1
	v_cndmask_b32_e64 v153, v153, v156, s[10:11]
	v_mul_f32_e32 v155, 0x37800000, v153
	v_cndmask_b32_e32 v153, v153, v155, vcc
	v_cmp_class_f32_e32 vcc, v154, v176
	s_nop 1
	v_cndmask_b32_e32 v153, v153, v154, vcc
	v_div_scale_f32 v156, s[10:11], v153, v153, s73
	v_rcp_f32_e32 v157, v156
	v_lshl_add_u64 v[154:155], s[30:31], 0, v[158:159]
	v_div_scale_f32 v158, vcc, s73, v153, s73
	v_fma_f32 v159, -v156, v157, 1.0
	v_fmac_f32_e32 v157, v159, v157
	v_mul_f32_e32 v159, v158, v157
	v_fma_f32 v160, -v156, v159, v158
	v_fmac_f32_e32 v159, v160, v157
	v_fma_f32 v156, -v156, v159, v158
	v_div_fmas_f32 v156, v156, v157, v159
	v_div_fixup_f32 v156, v156, v153, s73
	v_pk_mul_f32 v[160:161], v[80:81], v[156:157] op_sel_hi:[1,0]
	v_pk_mul_f32 v[164:165], v[78:79], v[156:157] op_sel_hi:[1,0]
	v_pk_mul_f32 v[158:159], v[76:77], v[156:157] op_sel_hi:[1,0]
	v_pk_mul_f32 v[162:163], v[74:75], v[156:157] op_sel_hi:[1,0]
	s_mov_b64 s[10:11], -1
	s_cbranch_scc1 .LBB0_1446
	global_load_dwordx4 v[180:183], v[154:155], off
	global_load_dwordx4 v[184:187], v[154:155], off offset:16
	global_load_dwordx4 v[188:191], v[154:155], off offset:32
	global_load_dwordx4 v[192:195], v[154:155], off offset:48
	v_and_b32_e32 v179, 64, v177
	v_xor_b32_e32 v157, 16, v177
	v_add_u32_e32 v179, 64, v179
	v_ashrrev_i32_e32 v153, 31, v152
	v_cmp_lt_i32_e32 vcc, v157, v179
	v_lshlrev_b64 v[196:197], 12, v[152:153]
	v_lshl_add_u64 v[196:197], v[196:197], 0, v[138:139]
	v_cndmask_b32_e32 v153, v177, v157, vcc
	v_lshlrev_b32_e32 v153, 2, v153
	ds_bpermute_b32 v157, v153, v164
	ds_bpermute_b32 v179, v153, v165
	ds_bpermute_b32 v199, v153, v160
	ds_bpermute_b32 v202, v153, v161
	ds_bpermute_b32 v204, v153, v162
	ds_bpermute_b32 v205, v153, v163
	ds_bpermute_b32 v206, v153, v158
	ds_bpermute_b32 v153, v153, v159
	v_mad_u64_u32 v[200:201], s[10:11], v196, s49, v[144:145]
	v_mad_i32_i24 v201, v197, s49, v201
	s_waitcnt lgkmcnt(0)
	v_cndmask_b32_e64 v197, v179, -v179, s[4:5]
	v_cndmask_b32_e64 v196, v157, -v157, s[4:5]
	v_cndmask_b32_e64 v203, v202, -v202, s[4:5]
	v_cndmask_b32_e64 v202, v199, -v199, s[4:5]
	v_cndmask_b32_e64 v205, v205, -v205, s[4:5]
	v_cndmask_b32_e64 v204, v204, -v204, s[4:5]
	v_cndmask_b32_e64 v207, v153, -v153, s[4:5]
	v_cndmask_b32_e64 v206, v206, -v206, s[4:5]
	s_mov_b64 s[10:11], 0
	s_waitcnt vmcnt(3)
	v_mov_b32_e32 v209, v182
	v_mov_b32_e32 v182, v181
	s_waitcnt vmcnt(2)
	v_mov_b32_e32 v181, v186
	v_mov_b32_e32 v186, v185
	s_waitcnt vmcnt(1)
	v_mov_b32_e32 v185, v190
	v_mov_b32_e32 v190, v189
	s_waitcnt vmcnt(0)
	v_mov_b32_e32 v189, v194
	v_mov_b32_e32 v194, v193
	v_mov_b32_e32 v208, v180
	v_mov_b32_e32 v180, v184
	v_mov_b32_e32 v184, v188
	v_mov_b32_e32 v188, v192
	v_pk_mul_f32 v[182:183], v[196:197], v[182:183]
	v_pk_mul_f32 v[186:187], v[202:203], v[186:187]
	v_pk_mul_f32 v[190:191], v[204:205], v[190:191]
	v_pk_mul_f32 v[192:193], v[206:207], v[194:195]
	v_pk_fma_f32 v[182:183], v[164:165], v[208:209], v[182:183]
	v_pk_fma_f32 v[186:187], v[160:161], v[180:181], v[186:187]
	v_pk_fma_f32 v[184:185], v[162:163], v[184:185], v[190:191]
	v_pk_fma_f32 v[188:189], v[158:159], v[188:189], v[192:193]
	v_cvt_pk_bf16_f32 v180, v182, v183
	v_cvt_pk_bf16_f32 v181, v186, v187
	v_cvt_pk_bf16_f32 v182, v184, v185
	v_cvt_pk_bf16_f32 v183, v188, v189
	global_store_dwordx4 v[200:201], v[180:183], off offset:128

.LBB0_1452:
	v_or_b32_e32 v150, 48, v150
	v_cmp_lt_i32_e32 vcc, s70, v150
	s_and_saveexec_b64 s[10:11], vcc
	s_xor_b64 s[10:11], exec, s[10:11]
	s_add_i32 s3, s2, 0xffffc000
	s_lshr_b32 s3, s3, 8
	v_or_b32_sdwa v138, v150, s66 dst_sel:DWORD dst_unused:UNUSED_PAD src0_sel:BYTE_0 src1_sel:DWORD
	v_mov_b32_e32 v152, s3
	s_andn2_saveexec_b64 s[10:11], s[10:11]
	s_ashr_i32 s2, s2, 12
	v_and_b32_e32 v138, 0xfff, v150
	v_mov_b32_e32 v152, s2
	s_or_b64 exec, exec, s[10:11]
	v_ashrrev_i32_e32 v151, 31, v150
	s_and_b64 vcc, exec, s[8:9]
	v_lshlrev_b64 v[150:151], 4, v[150:151]
	s_cbranch_vccnz .LBB0_1458
	v_and_b32_e32 v246, 0xff0, v150
	v_lshl_add_u64 v[154:155], s[28:29], 0, v[150:151]
	v_add_u32_e32 v246, v247, v246
	ds_read_b128 v[154:157], v246
	s_lshl_b32 s2, s38, 8
	s_or_b32 s2, s2, s63
	s_ashr_i32 s2, s2, 6
	v_lshl_add_u32 v153, v152, 3, s2
	v_mad_i64_i32 v[158:159], s[2:3], v153, s72, v[138:139]
	v_or_b32_e32 v153, 2, v153
	v_mad_i64_i32 v[160:161], s[2:3], v153, s72, v[138:139]
	v_mad_u64_u32 v[162:163], s[2:3], v158, s49, v[140:141]
	v_mad_i32_i24 v163, v159, s49, v163
	s_waitcnt lgkmcnt(0)
	v_mov_b32_e32 v164, v155
	v_mov_b32_e32 v165, v156
	v_mov_b32_e32 v155, v157
	v_pk_add_f32 v[154:155], v[164:165], v[154:155]
	v_mad_u64_u32 v[164:165], s[2:3], v160, s49, v[140:141]
	v_add_f32_e32 v153, v154, v155
	v_fmamk_f32 v153, v153, 0x3c000000, v175
	v_mul_f32_e32 v154, 0x4f800000, v153
	v_cmp_gt_f32_e32 vcc, s71, v153
	v_mad_i32_i24 v165, v161, s49, v165
	s_nop 0
	v_cndmask_b32_e32 v153, v153, v154, vcc
	v_sqrt_f32_e32 v154, v153
	s_nop 0
	v_add_u32_e32 v155, -1, v154
	v_add_u32_e32 v156, 1, v154
	v_fma_f32 v157, -v155, v154, v153
	v_fma_f32 v158, -v156, v154, v153
	v_cmp_ge_f32_e64 s[8:9], 0, v157
	s_nop 1
	v_cndmask_b32_e64 v154, v154, v155, s[8:9]
	v_cmp_lt_f32_e64 s[8:9], 0, v158
	s_nop 1
	v_cndmask_b32_e64 v154, v154, v156, s[8:9]
	v_mul_f32_e32 v155, 0x37800000, v154
	v_cndmask_b32_e32 v154, v154, v155, vcc
	v_cmp_class_f32_e32 vcc, v153, v176
	s_nop 1
	v_cndmask_b32_e32 v153, v154, v153, vcc
	v_div_scale_f32 v154, s[2:3], v153, v153, 1.0
	v_rcp_f32_e32 v155, v154
	v_div_scale_f32 v156, vcc, 1.0, v153, 1.0
	v_fma_f32 v157, -v154, v155, 1.0
	v_fmac_f32_e32 v155, v157, v155
	v_mul_f32_e32 v157, v156, v155
	v_fma_f32 v158, -v154, v157, v156
	v_fmac_f32_e32 v157, v158, v155
	v_fma_f32 v154, -v154, v157, v156
	v_div_fmas_f32 v154, v154, v155, v157
	v_div_fixup_f32 v154, v154, v153, 1.0
	v_pk_mul_f32 v[156:157], v[72:73], v[154:155] op_sel_hi:[1,0]
	v_pk_mul_f32 v[158:159], v[70:71], v[154:155] op_sel_hi:[1,0]
	v_pk_mul_f32 v[160:161], v[68:69], v[154:155] op_sel_hi:[1,0]
	v_pk_mul_f32 v[180:181], v[66:67], v[154:155] op_sel_hi:[1,0]
	v_pk_mul_f32 v[182:183], v[8:9], v[154:155] op_sel_hi:[1,0]
	v_pk_mul_f32 v[184:185], v[6:7], v[154:155] op_sel_hi:[1,0]
	v_pk_mul_f32 v[186:187], v[4:5], v[154:155] op_sel_hi:[1,0]
	v_pk_mul_f32 v[188:189], v[2:3], v[154:155] op_sel_hi:[1,0]
	v_cvt_pk_bf16_f32 v154, v158, v159
	v_cvt_pk_bf16_f32 v155, v156, v157
	v_cvt_pk_bf16_f32 v156, v180, v181
	v_cvt_pk_bf16_f32 v157, v160, v161
	v_cvt_pk_bf16_f32 v158, v184, v185
	v_cvt_pk_bf16_f32 v159, v182, v183
	v_cvt_pk_bf16_f32 v160, v188, v189
	v_cvt_pk_bf16_f32 v161, v186, v187
	global_store_dwordx4 v[162:163], v[154:157], off
	global_store_dwordx4 v[164:165], v[158:161], off
	s_cbranch_execz .LBB0_1459
	s_branch .LBB0_1467
.LBB0_1458:
.LBB0_1459:
	v_and_b32_e32 v246, 0xff0, v150
	v_lshl_add_u64 v[150:151], s[34:35], 0, v[150:151]
	v_add_u32_e32 v246, v247, v246
	ds_read_b128 v[154:157], v246
	v_lshlrev_b32_e32 v164, 3, v152
	v_lshrrev_b32_e32 v150, 6, v138
	v_and_b32_e32 v151, 63, v138
	v_cndmask_b32_e64 v151, v151, v150, s[0:1]
	v_mov_b32_e32 v153, v139
	s_cmp_gt_i32 s38, 1
	v_or_b32_e32 v150, s60, v164
	s_cselect_b64 s[10:11], -1, 0
	s_cmp_lt_i32 s38, 2
	s_waitcnt lgkmcnt(0)
	v_mov_b32_e32 v158, v155
	v_mov_b32_e32 v159, v156
	v_mov_b32_e32 v155, v157
	v_pk_add_f32 v[154:155], v[158:159], v[154:155]
	s_nop 0
	v_add_f32_e32 v152, v154, v155
	v_fmamk_f32 v152, v152, 0x3b800000, v175
	v_mul_f32_e32 v154, 0x4f800000, v152
	v_cmp_gt_f32_e32 vcc, s71, v152
	s_nop 1
	v_cndmask_b32_e32 v154, v152, v154, vcc
	v_sqrt_f32_e32 v155, v154
	v_lshlrev_b32_e32 v152, 6, v151
	v_lshl_add_u64 v[152:153], s[30:31], 0, v[152:153]
	v_add_u32_e32 v151, -1, v155
	v_add_u32_e32 v156, 1, v155
	v_fma_f32 v157, -v151, v155, v154
	v_fma_f32 v158, -v156, v155, v154
	v_cmp_ge_f32_e64 s[8:9], 0, v157
	s_nop 1
	v_cndmask_b32_e64 v151, v155, v151, s[8:9]
	v_cmp_lt_f32_e64 s[8:9], 0, v158
	s_nop 1
	v_cndmask_b32_e64 v151, v151, v156, s[8:9]
	v_mul_f32_e32 v155, 0x37800000, v151
	v_cndmask_b32_e32 v151, v151, v155, vcc
	v_cmp_class_f32_e32 vcc, v154, v176
	s_mov_b64 s[8:9], -1
	s_nop 0
	v_cndmask_b32_e32 v151, v151, v154, vcc
	v_div_scale_f32 v154, s[2:3], v151, v151, s73
	v_rcp_f32_e32 v155, v154
	v_div_scale_f32 v156, vcc, s73, v151, s73
	v_fma_f32 v157, -v154, v155, 1.0
	v_fmac_f32_e32 v155, v157, v155
	v_mul_f32_e32 v157, v156, v155
	v_fma_f32 v158, -v154, v157, v156
	v_fmac_f32_e32 v157, v158, v155
	v_fma_f32 v154, -v154, v157, v156
	v_div_fmas_f32 v154, v154, v155, v157
	v_div_fixup_f32 v154, v154, v151, s73
	v_pk_mul_f32 v[158:159], v[72:73], v[154:155] op_sel_hi:[1,0]
	v_pk_mul_f32 v[162:163], v[70:71], v[154:155] op_sel_hi:[1,0]
	v_pk_mul_f32 v[156:157], v[68:69], v[154:155] op_sel_hi:[1,0]
	v_pk_mul_f32 v[160:161], v[66:67], v[154:155] op_sel_hi:[1,0]
	s_cbranch_scc1 .LBB0_1461
	global_load_dwordx4 v[180:183], v[152:153], off
	global_load_dwordx4 v[184:187], v[152:153], off offset:16
	global_load_dwordx4 v[188:191], v[152:153], off offset:32
	global_load_dwordx4 v[192:195], v[152:153], off offset:48
	v_and_b32_e32 v165, 64, v177
	v_xor_b32_e32 v155, 16, v177
	v_add_u32_e32 v165, 64, v165
	v_ashrrev_i32_e32 v151, 31, v150
	v_cmp_lt_i32_e32 vcc, v155, v165
	v_lshlrev_b64 v[196:197], 12, v[150:151]
	v_lshl_add_u64 v[196:197], v[196:197], 0, v[138:139]
	v_cndmask_b32_e32 v151, v177, v155, vcc
	v_lshlrev_b32_e32 v151, 2, v151
	ds_bpermute_b32 v155, v151, v162
	ds_bpermute_b32 v165, v151, v163
	ds_bpermute_b32 v179, v151, v158
	ds_bpermute_b32 v199, v151, v159
	ds_bpermute_b32 v204, v151, v160
	ds_bpermute_b32 v205, v151, v161
	ds_bpermute_b32 v206, v151, v156
	ds_bpermute_b32 v151, v151, v157
	v_mad_u64_u32 v[200:201], s[2:3], v196, s49, v[144:145]
	v_mad_i32_i24 v201, v197, s49, v201
	s_waitcnt lgkmcnt(0)
	v_cndmask_b32_e64 v197, v165, -v165, s[4:5]
	v_cndmask_b32_e64 v196, v155, -v155, s[4:5]
	v_cndmask_b32_e64 v203, v199, -v199, s[4:5]
	v_cndmask_b32_e64 v202, v179, -v179, s[4:5]
	v_cndmask_b32_e64 v205, v205, -v205, s[4:5]
	v_cndmask_b32_e64 v204, v204, -v204, s[4:5]
	v_cndmask_b32_e64 v207, v151, -v151, s[4:5]
	v_cndmask_b32_e64 v206, v206, -v206, s[4:5]
	s_mov_b64 s[8:9], 0
	s_waitcnt vmcnt(3)
	v_mov_b32_e32 v209, v182
	v_mov_b32_e32 v182, v181
	s_waitcnt vmcnt(2)
	v_mov_b32_e32 v181, v186
	v_mov_b32_e32 v186, v185
	s_waitcnt vmcnt(1)
	v_mov_b32_e32 v185, v190
	v_mov_b32_e32 v190, v189
	s_waitcnt vmcnt(0)
	v_mov_b32_e32 v189, v194
	v_mov_b32_e32 v194, v193
	v_mov_b32_e32 v208, v180
	v_mov_b32_e32 v180, v184
	v_mov_b32_e32 v184, v188
	v_mov_b32_e32 v188, v192
	v_pk_mul_f32 v[182:183], v[196:197], v[182:183]
	v_pk_mul_f32 v[186:187], v[202:203], v[186:187]
	v_pk_mul_f32 v[190:191], v[204:205], v[190:191]
	v_pk_mul_f32 v[192:193], v[206:207], v[194:195]
	v_pk_fma_f32 v[182:183], v[162:163], v[208:209], v[182:183]
	v_pk_fma_f32 v[186:187], v[158:159], v[180:181], v[186:187]
	v_pk_fma_f32 v[184:185], v[160:161], v[184:185], v[190:191]
	v_pk_fma_f32 v[188:189], v[156:157], v[188:189], v[192:193]
	v_cvt_pk_bf16_f32 v180, v182, v183
	v_cvt_pk_bf16_f32 v181, v186, v187
	v_cvt_pk_bf16_f32 v182, v184, v185
	v_cvt_pk_bf16_f32 v183, v188, v189
	global_store_dwordx4 v[200:201], v[180:183], off offset:128
